# rss via Gram MFMAs (diag of A*A^T, 4 per wave per K-step, split by k-half between wn waves, ds_add_f32 combine) instead of v_dot2c; grid.sync replaced by XCD barrier
# speedup vs baseline: 1.0925x; 1.0164x over previous
; DI void lds_barrier() { asm volatile("s_waitcnt lgkmcnt(0)\n\ts_barrier" ::: "memory"); }
; #define G_LOAD(RA, RB, KT) { size_t as_ = astep, bs_ = bstep; asm volatile("" : "+s"(as_), "+s"(bs_)); \
;       _Pragma("unroll") for (int i = 0; i < 4; ++i) { RA[i] = *(const u32x4*)(Ag + i * as_ + (KT) * 64); RB[i] = *(const u32x4*)(Bg + i * bs_ + (KT) * 64); } }
; DI void gemm_run(const GemmCfg c, char* smem, float* const g_h, u16* const g_hb, float* const g_out, const int final_out) {
;     ...
;   for (int slot = Lb; slot < ntiles; slot += G) {
;     const int sr = slot / srow, idx = slot - sr * srow;
;     const int tm = sr < 8 ? sr * 8 + (idx & 7) : 64;
;     const int tn = sr < 8 ? (idx >> 3) : idx;
;     const u16* Ag = c.A + (size_t)(tm * 256 + lrow) * c.lda + tn * c.a_koff_tn + lch * 8;
;     const u16* Bg = c.Bt + (size_t)(tn * 256 + lrow) * K + lch * 8;
;     const size_t astep = (size_t)64 * c.lda, bstep = (size_t)64 * K;
;     f32x16 acc[2][4];
; #pragma unroll
;     for (int a = 0; a < 2; ++a)
; #pragma unroll
;       for (int b = 0; b < 4; ++b)
; #pragma unroll
;         for (int i = 0; i < 16; ++i) acc[a][b][i] = 0.f;
;     float ss[4] = {0.f, 0.f, 0.f, 0.f};
;     u32x4 ra0[4], rb0[4];
;     ...
;     G_LOAD(ra0, rb0, 0);
;     __syncthreads();
;     G_STORE(ra0, rb0, 0);
;     G_LOAD(ra0, rb0, 1);
;     lds_barrier();
.LBB0_110:
	s_abs_i32 s1, s48
	s_mul_hi_u32 s4, s1, s69
	s_mul_i32 s5, s4, s30
	s_ashr_i32 s0, s48, 31
	s_sub_i32 s1, s1, s5
	s_xor_b32 s0, s0, s63
	s_add_i32 s5, s4, 1
	s_sub_i32 s6, s1, s30
	s_cmp_ge_u32 s1, s30
	s_cselect_b32 s4, s5, s4
	s_cselect_b32 s1, s6, s1
	s_add_i32 s5, s4, 1
	s_cmp_ge_u32 s1, s30
	s_cselect_b32 s1, s5, s4
	s_xor_b32 s1, s1, s0
	s_sub_i32 s0, s1, s0
	s_mul_i32 s1, s0, s65
	s_sub_i32 s1, s48, s1
	s_lshl_b32 s4, s0, 3
	s_and_b32 s5, s48, 7
	s_or_b32 s4, s4, s5
	s_ashr_i32 s5, s1, 3
	s_cmp_lt_i32 s0, 8
	s_cselect_b32 s78, s4, 64
	s_waitcnt lgkmcnt(0)
	s_cselect_b32 s49, s5, s1
	v_lshrrev_b32_e32 v128, 3, v185
	v_and_b32_e32 v129, 7, v185
	v_xor_b32_e32 v129, v129, v128
	v_lshlrev_b32_e32 v129, 4, v129
	s_lshl_b32 s0, s62, 1
	v_mul_lo_u32 v130, v128, s0
	s_lshl_b32 s1, s62, 4
	v_add_u32_e32 v130, v130, v129
	v_add_u32_e32 v131, s1, v130
	v_add_u32_e32 v132, s1, v131
	v_add_u32_e32 v133, s1, v132
	s_lshl_b32 s0, s60, 1
	v_mul_lo_u32 v134, v128, s0
	s_lshl_b32 s1, s60, 4
	v_add_u32_e32 v134, v134, v129
	v_add_u32_e32 v135, s1, v134
	v_add_u32_e32 v136, s1, v135
	v_add_u32_e32 v137, s1, v136
	s_lshl_b32 s8, s75, 5
	s_add_i32 s8, s8, s86
	s_lshl_b32 s0, s78, 8
	s_add_i32 s0, s0, s8
	s_mul_i32 s0, s0, s62
	s_mul_i32 s1, s49, s2
	s_add_i32 s0, s0, s1
	s_lshl_b32 s0, s0, 1
	s_add_u32 s4, s54, s0
	s_addc_u32 s5, s55, 0
	v_readlane_b32 s6, v255, 5
	v_readlane_b32 s7, v255, 6
	s_lshl_b32 s0, s49, 8
	s_add_i32 s0, s0, s8
	s_mul_i32 s0, s0, s60
	s_lshl_b32 s0, s0, 1
	s_add_u32 s6, s6, s0
	s_addc_u32 s7, s7, 0
	s_lshl_b32 s8, s8, 7
	s_add_i32 s9, s75, 1
	s_and_b32 s9, s9, s88
	s_barrier
	s_cmp_lt_u32 s8, 0x4000
	s_cbranch_scc0 .Lgemm_rz_skip
	v_lshlrev_b32_e32 v128, 2, v185
	s_lshr_b32 s1, s8, 4
	s_add_i32 s1, s1, 0x24000
	v_mov_b32_e32 v129, 0
	v_add_u32_e32 v128, s1, v128
	ds_write_b32 v128, v129
.Lgemm_rz_skip:
	s_add_u32 m0, s8, 0x0
	s_nop 0
	global_load_lds_dwordx4 v130, s[4:5]
	s_add_u32 m0, s8, 0x12000
	s_nop 0
	global_load_lds_dwordx4 v134, s[6:7]
	s_add_u32 m0, s8, 0x400
	s_nop 0
	global_load_lds_dwordx4 v131, s[4:5]
	s_add_u32 m0, s8, 0x12400
	s_nop 0
	global_load_lds_dwordx4 v135, s[6:7]
	s_add_u32 m0, s8, 0x800
	s_nop 0
	global_load_lds_dwordx4 v132, s[4:5]
	s_add_u32 m0, s8, 0x12800
	s_nop 0
	global_load_lds_dwordx4 v136, s[6:7]
	s_add_u32 m0, s8, 0xc00
	s_nop 0
	global_load_lds_dwordx4 v133, s[4:5]
	s_add_u32 m0, s8, 0x12c00
	s_nop 0
	global_load_lds_dwordx4 v137, s[6:7]
	s_add_u32 s4, s4, 0x80
	s_addc_u32 s5, s5, 0
	s_add_u32 s6, s6, 0x80
	s_addc_u32 s7, s7, 0
	s_add_u32 m0, s8, 0x9000
	s_nop 0
	global_load_lds_dwordx4 v130, s[4:5]
	s_add_u32 m0, s8, 0x1b000
	s_nop 0
	global_load_lds_dwordx4 v134, s[6:7]
	s_add_u32 m0, s8, 0x9400
	s_nop 0
	global_load_lds_dwordx4 v131, s[4:5]
	s_add_u32 m0, s8, 0x1b400
	s_nop 0
	global_load_lds_dwordx4 v135, s[6:7]
	s_add_u32 m0, s8, 0x9800
	s_nop 0
	global_load_lds_dwordx4 v132, s[4:5]
	s_add_u32 m0, s8, 0x1b800
	s_nop 0
	global_load_lds_dwordx4 v136, s[6:7]
	s_add_u32 m0, s8, 0x9c00
	s_nop 0
	global_load_lds_dwordx4 v133, s[4:5]
	s_add_u32 m0, s8, 0x1bc00
	s_nop 0
	global_load_lds_dwordx4 v137, s[6:7]
	s_add_u32 s4, s4, 0x80
	s_addc_u32 s5, s5, 0
	s_add_u32 s6, s6, 0x80
	s_addc_u32 s7, s7, 0
	v_mov_b32_e32 v0, 0
	v_mov_b32_e32 v1, 0
	v_mov_b32_e32 v2, 0
	v_mov_b32_e32 v3, 0
	v_mov_b32_e32 v4, 0
	v_mov_b32_e32 v5, 0
	v_mov_b32_e32 v6, 0
	v_mov_b32_e32 v7, 0
	v_mov_b32_e32 v8, 0
	v_mov_b32_e32 v9, 0
	v_mov_b32_e32 v10, 0
	v_mov_b32_e32 v11, 0
	v_mov_b32_e32 v12, 0
	v_mov_b32_e32 v13, 0
	v_mov_b32_e32 v14, 0
	v_mov_b32_e32 v15, 0
	v_mov_b32_e32 v16, 0
	v_mov_b32_e32 v17, 0
	v_mov_b32_e32 v18, 0
	v_mov_b32_e32 v19, 0
	v_mov_b32_e32 v20, 0
	v_mov_b32_e32 v21, 0
	v_mov_b32_e32 v22, 0
	v_mov_b32_e32 v23, 0
	v_mov_b32_e32 v24, 0
	v_mov_b32_e32 v25, 0
	v_mov_b32_e32 v26, 0
	v_mov_b32_e32 v27, 0
	v_mov_b32_e32 v28, 0
	v_mov_b32_e32 v29, 0
	v_mov_b32_e32 v30, 0
	v_mov_b32_e32 v31, 0
	v_mov_b32_e32 v32, 0
	v_mov_b32_e32 v33, 0
	v_mov_b32_e32 v34, 0
	v_mov_b32_e32 v35, 0
	v_mov_b32_e32 v36, 0
	v_mov_b32_e32 v37, 0
	v_mov_b32_e32 v38, 0
	v_mov_b32_e32 v39, 0
	v_mov_b32_e32 v40, 0
	v_mov_b32_e32 v41, 0
	v_mov_b32_e32 v42, 0
	v_mov_b32_e32 v43, 0
	v_mov_b32_e32 v44, 0
	v_mov_b32_e32 v45, 0
	v_mov_b32_e32 v46, 0
	v_mov_b32_e32 v47, 0
	v_mov_b32_e32 v48, 0
	v_mov_b32_e32 v49, 0
	v_mov_b32_e32 v50, 0
	v_mov_b32_e32 v51, 0
	v_mov_b32_e32 v52, 0
	v_mov_b32_e32 v53, 0
	v_mov_b32_e32 v54, 0
	v_mov_b32_e32 v55, 0
	v_mov_b32_e32 v56, 0
	v_mov_b32_e32 v57, 0
	v_mov_b32_e32 v58, 0
	v_mov_b32_e32 v59, 0
	v_mov_b32_e32 v60, 0
	v_mov_b32_e32 v61, 0
	v_mov_b32_e32 v62, 0
	v_mov_b32_e32 v63, 0
	v_mov_b32_e32 v64, 0
	v_mov_b32_e32 v65, 0
	v_mov_b32_e32 v66, 0
	v_mov_b32_e32 v67, 0
	v_mov_b32_e32 v68, 0
	v_mov_b32_e32 v69, 0
	v_mov_b32_e32 v70, 0
	v_mov_b32_e32 v71, 0
	v_mov_b32_e32 v72, 0
	v_mov_b32_e32 v73, 0
	v_mov_b32_e32 v74, 0
	v_mov_b32_e32 v75, 0
	v_mov_b32_e32 v76, 0
	v_mov_b32_e32 v77, 0
	v_mov_b32_e32 v78, 0
	v_mov_b32_e32 v79, 0
	v_mov_b32_e32 v80, 0
	v_mov_b32_e32 v81, 0
	v_mov_b32_e32 v82, 0
	v_mov_b32_e32 v83, 0
	v_mov_b32_e32 v84, 0
	v_mov_b32_e32 v85, 0
	v_mov_b32_e32 v86, 0
	v_mov_b32_e32 v87, 0
	v_mov_b32_e32 v88, 0
	v_mov_b32_e32 v89, 0
	v_mov_b32_e32 v90, 0
	v_mov_b32_e32 v91, 0
	v_mov_b32_e32 v92, 0
	v_mov_b32_e32 v93, 0
	v_mov_b32_e32 v94, 0
	v_mov_b32_e32 v95, 0
	v_mov_b32_e32 v96, 0
	v_mov_b32_e32 v97, 0
	v_mov_b32_e32 v98, 0
	v_mov_b32_e32 v99, 0
	v_mov_b32_e32 v100, 0
	v_mov_b32_e32 v101, 0
	v_mov_b32_e32 v102, 0
	v_mov_b32_e32 v103, 0
	v_mov_b32_e32 v104, 0
	v_mov_b32_e32 v105, 0
	v_mov_b32_e32 v106, 0
	v_mov_b32_e32 v107, 0
	v_mov_b32_e32 v108, 0
	v_mov_b32_e32 v109, 0
	v_mov_b32_e32 v110, 0
	v_mov_b32_e32 v111, 0
	v_mov_b32_e32 v112, 0
	v_mov_b32_e32 v113, 0
	v_mov_b32_e32 v114, 0
	v_mov_b32_e32 v115, 0
	v_mov_b32_e32 v116, 0
	v_mov_b32_e32 v117, 0
	v_mov_b32_e32 v118, 0
	v_mov_b32_e32 v119, 0
	v_mov_b32_e32 v120, 0
	v_mov_b32_e32 v121, 0
	v_mov_b32_e32 v122, 0
	v_mov_b32_e32 v123, 0
	v_mov_b32_e32 v124, 0
	v_mov_b32_e32 v125, 0
	v_mov_b32_e32 v126, 0
	v_mov_b32_e32 v127, 0
	v_mov_b32_e32 v199, 0
	v_mov_b32_e32 v198, 0
	v_mov_b32_e32 v171, 0
	v_mov_b32_e32 v164, 0
	v_mov_b32_e32 v140, 0
	v_mov_b32_e32 v141, 0
	v_mov_b32_e32 v142, 0
	v_mov_b32_e32 v143, 0
	v_mov_b32_e32 v144, 0
	v_mov_b32_e32 v145, 0
	v_mov_b32_e32 v146, 0
	v_mov_b32_e32 v147, 0
	v_mov_b32_e32 v148, 0
	v_mov_b32_e32 v149, 0
	v_mov_b32_e32 v150, 0
	v_mov_b32_e32 v151, 0
	v_mov_b32_e32 v152, 0
	v_mov_b32_e32 v153, 0
	v_mov_b32_e32 v154, 0
	v_mov_b32_e32 v155, 0
	s_mov_b32 s1, 0
	s_add_i32 s0, s68, 3
	s_waitcnt vmcnt(8)
	s_barrier
; DI void lds_barrier() { asm volatile("s_waitcnt lgkmcnt(0)\n\ts_barrier" ::: "memory"); }
; #define G_LOAD(RA, RB, KT) { size_t as_ = astep, bs_ = bstep; asm volatile("" : "+s"(as_), "+s"(bs_)); \
;       _Pragma("unroll") for (int i = 0; i < 4; ++i) { RA[i] = *(const u32x4*)(Ag + i * as_ + (KT) * 64); RB[i] = *(const u32x4*)(Bg + i * bs_ + (KT) * 64); } }
; DI void gemm_run(const GemmCfg c, char* smem, float* const g_h, u16* const g_hb, float* const g_out, const int final_out) {
;     ...
;     G_LOAD(ra0, rb0, 0);
;     __syncthreads();
;     G_STORE(ra0, rb0, 0);
;     G_LOAD(ra0, rb0, 1);
;     lds_barrier();
;     int kt = 0;
;     for (; kt + 3 < nk; kt += 2) {
;       K_STEP(0, 1, kt + 2, true, true);
;       lds_barrier();
;       K_STEP(1, 0, kt + 3, true, true);
;       lds_barrier();
;     }
	ds_read_b128 v[160:163], v194
	ds_read_b128 v[176:179], v194 offset:2048
	ds_read_b128 v[180:183], v194 offset:4096
	ds_read_b128 v[204:207], v195
	ds_read_b128 v[222:225], v195 offset:2048
	ds_read_b128 v[226:229], v195 offset:4096
	ds_read_b128 v[230:233], v195 offset:6144
	ds_read_b128 v[234:237], v195 offset:8192
	ds_read_b128 v[238:241], v195 offset:10240
	ds_read_b128 v[242:245], v195 offset:12288
	ds_read_b128 v[246:249], v195 offset:14336
	ds_read_b128 v[200:203], v194 offset:6144
	s_cmp_ge_u32 s8, 0x4000
	s_cbranch_scc1 .Lgemm_disp_late
	s_cmp_eq_u32 s9, 0
	s_cbranch_scc1 .Lgemm_kloop_n
	s_cmp_eq_u32 s9, 2
	s_cbranch_scc1 .Lgemm_kloop_r1e
	s_branch .LBB0_112
.Lgemm_disp_late:
	s_cmp_eq_u32 s9, 0
	s_cbranch_scc1 .Lgemm_kloop_nl
	s_cmp_eq_u32 s9, 2
	s_cbranch_scc1 .Lgemm_kloop_r1l
	s_branch .Lgemm_kloop_rl
.LBB0_112:
	s_waitcnt lgkmcnt(8)
	v_mfma_f32_16x16x32_bf16 v[64:67], v[160:163], v[204:207], v[64:67]
	s_waitcnt lgkmcnt(7)
	v_mfma_f32_16x16x32_bf16 v[68:71], v[160:163], v[222:225], v[68:71]
	s_waitcnt lgkmcnt(6)
	v_mfma_f32_16x16x32_bf16 v[72:75], v[160:163], v[226:229], v[72:75]
	v_mfma_f32_16x16x32_bf16 v[140:143], v[160:163], v[160:163], v[140:143]
	s_waitcnt lgkmcnt(5)
	v_mfma_f32_16x16x32_bf16 v[76:79], v[160:163], v[230:233], v[76:79]
	s_waitcnt lgkmcnt(4)
	v_mfma_f32_16x16x32_bf16 v[80:83], v[160:163], v[234:237], v[80:83]
	s_waitcnt lgkmcnt(3)
	v_mfma_f32_16x16x32_bf16 v[84:87], v[160:163], v[238:241], v[84:87]
	s_waitcnt lgkmcnt(2)
	v_mfma_f32_16x16x32_bf16 v[88:91], v[160:163], v[242:245], v[88:91]
	s_waitcnt lgkmcnt(1)
	v_mfma_f32_16x16x32_bf16 v[92:95], v[160:163], v[246:249], v[92:95]
	ds_read_b128 v[160:163], v215
	v_mfma_f32_16x16x32_bf16 v[96:99], v[176:179], v[204:207], v[96:99]
	v_mfma_f32_16x16x32_bf16 v[100:103], v[176:179], v[222:225], v[100:103]
	v_mfma_f32_16x16x32_bf16 v[104:107], v[176:179], v[226:229], v[104:107]
	v_mfma_f32_16x16x32_bf16 v[144:147], v[176:179], v[176:179], v[144:147]
	v_mfma_f32_16x16x32_bf16 v[108:111], v[176:179], v[230:233], v[108:111]
	v_mfma_f32_16x16x32_bf16 v[112:115], v[176:179], v[234:237], v[112:115]
	v_mfma_f32_16x16x32_bf16 v[116:119], v[176:179], v[238:241], v[116:119]
	v_mfma_f32_16x16x32_bf16 v[120:123], v[176:179], v[242:245], v[120:123]
	v_mfma_f32_16x16x32_bf16 v[124:127], v[176:179], v[246:249], v[124:127]
	ds_read_b128 v[176:179], v215 offset:2048
	v_mfma_f32_16x16x32_bf16 v[0:3], v[180:183], v[204:207], v[0:3]
	v_mfma_f32_16x16x32_bf16 v[4:7], v[180:183], v[222:225], v[4:7]
	v_mfma_f32_16x16x32_bf16 v[8:11], v[180:183], v[226:229], v[8:11]
	v_mfma_f32_16x16x32_bf16 v[148:151], v[180:183], v[180:183], v[148:151]
	v_mfma_f32_16x16x32_bf16 v[12:15], v[180:183], v[230:233], v[12:15]
	v_mfma_f32_16x16x32_bf16 v[16:19], v[180:183], v[234:237], v[16:19]
	v_mfma_f32_16x16x32_bf16 v[20:23], v[180:183], v[238:241], v[20:23]
	v_mfma_f32_16x16x32_bf16 v[24:27], v[180:183], v[242:245], v[24:27]
	v_mfma_f32_16x16x32_bf16 v[28:31], v[180:183], v[246:249], v[28:31]
	ds_read_b128 v[180:183], v215 offset:4096
	s_waitcnt lgkmcnt(3)
	v_mfma_f32_16x16x32_bf16 v[32:35], v[200:203], v[204:207], v[32:35]
	ds_read_b128 v[204:207], v197
	v_mfma_f32_16x16x32_bf16 v[36:39], v[200:203], v[222:225], v[36:39]
	ds_read_b128 v[222:225], v197 offset:2048
	v_mfma_f32_16x16x32_bf16 v[40:43], v[200:203], v[226:229], v[40:43]
	v_mfma_f32_16x16x32_bf16 v[152:155], v[200:203], v[200:203], v[152:155]
	ds_read_b128 v[226:229], v197 offset:4096
	v_mfma_f32_16x16x32_bf16 v[44:47], v[200:203], v[230:233], v[44:47]
	ds_read_b128 v[230:233], v197 offset:6144
	v_mfma_f32_16x16x32_bf16 v[48:51], v[200:203], v[234:237], v[48:51]
	ds_read_b128 v[234:237], v197 offset:8192
	v_mfma_f32_16x16x32_bf16 v[52:55], v[200:203], v[238:241], v[52:55]
	ds_read_b128 v[238:241], v197 offset:10240
	v_mfma_f32_16x16x32_bf16 v[56:59], v[200:203], v[242:245], v[56:59]
	ds_read_b128 v[242:245], v197 offset:12288
	v_mfma_f32_16x16x32_bf16 v[60:63], v[200:203], v[246:249], v[60:63]
	ds_read_b128 v[246:249], v197 offset:14336
	ds_read_b128 v[200:203], v215 offset:6144
	s_waitcnt lgkmcnt(8)
	v_mfma_f32_16x16x32_bf16 v[64:67], v[160:163], v[204:207], v[64:67]
	s_waitcnt lgkmcnt(7)
	v_mfma_f32_16x16x32_bf16 v[68:71], v[160:163], v[222:225], v[68:71]
	s_waitcnt lgkmcnt(6)
	v_mfma_f32_16x16x32_bf16 v[72:75], v[160:163], v[226:229], v[72:75]
	s_waitcnt lgkmcnt(5)
	v_mfma_f32_16x16x32_bf16 v[76:79], v[160:163], v[230:233], v[76:79]
	s_waitcnt lgkmcnt(4)
	v_mfma_f32_16x16x32_bf16 v[80:83], v[160:163], v[234:237], v[80:83]
	s_waitcnt lgkmcnt(3)
	v_mfma_f32_16x16x32_bf16 v[84:87], v[160:163], v[238:241], v[84:87]
	s_waitcnt lgkmcnt(2)
	v_mfma_f32_16x16x32_bf16 v[88:91], v[160:163], v[242:245], v[88:91]
	s_waitcnt lgkmcnt(1)
	v_mfma_f32_16x16x32_bf16 v[92:95], v[160:163], v[246:249], v[92:95]
	s_waitcnt vmcnt(0) lgkmcnt(0)
	s_barrier
; DI void lds_barrier() { asm volatile("s_waitcnt lgkmcnt(0)\n\ts_barrier" ::: "memory"); }
; #define G_LOAD(RA, RB, KT) { size_t as_ = astep, bs_ = bstep; asm volatile("" : "+s"(as_), "+s"(bs_)); \
;       _Pragma("unroll") for (int i = 0; i < 4; ++i) { RA[i] = *(const u32x4*)(Ag + i * as_ + (KT) * 64); RB[i] = *(const u32x4*)(Bg + i * bs_ + (KT) * 64); } }
; DI void gemm_run(const GemmCfg c, char* smem, float* const g_h, u16* const g_hb, float* const g_out, const int final_out) {
;     ...
;     G_LOAD(ra0, rb0, 0);
;     __syncthreads();
;     G_STORE(ra0, rb0, 0);
;     G_LOAD(ra0, rb0, 1);
;     lds_barrier();
;     int kt = 0;
;     for (; kt + 3 < nk; kt += 2) {
;       K_STEP(0, 1, kt + 2, true, true);
;       lds_barrier();
;       K_STEP(1, 0, kt + 3, true, true);
;       lds_barrier();
;     }
	s_add_u32 m0, s8, 0x0
	ds_read_b128 v[160:163], v194 offset:36864
	v_mfma_f32_16x16x32_bf16 v[96:99], v[176:179], v[204:207], v[96:99]
	global_load_lds_dwordx4 v130, s[4:5]
	s_add_u32 m0, s8, 0x12000
	v_mfma_f32_16x16x32_bf16 v[100:103], v[176:179], v[222:225], v[100:103]
	global_load_lds_dwordx4 v134, s[6:7]
	s_add_u32 m0, s8, 0x400
	v_mfma_f32_16x16x32_bf16 v[104:107], v[176:179], v[226:229], v[104:107]
	global_load_lds_dwordx4 v131, s[4:5]
	s_add_u32 m0, s8, 0x12400
	v_mfma_f32_16x16x32_bf16 v[108:111], v[176:179], v[230:233], v[108:111]
	global_load_lds_dwordx4 v135, s[6:7]
	s_add_u32 m0, s8, 0x800
	v_mfma_f32_16x16x32_bf16 v[112:115], v[176:179], v[234:237], v[112:115]
	global_load_lds_dwordx4 v132, s[4:5]
	s_add_u32 m0, s8, 0x12800
	v_mfma_f32_16x16x32_bf16 v[116:119], v[176:179], v[238:241], v[116:119]
	global_load_lds_dwordx4 v136, s[6:7]
	s_add_u32 m0, s8, 0xc00
	v_mfma_f32_16x16x32_bf16 v[120:123], v[176:179], v[242:245], v[120:123]
	global_load_lds_dwordx4 v133, s[4:5]
	s_add_u32 m0, s8, 0x12c00
	v_mfma_f32_16x16x32_bf16 v[124:127], v[176:179], v[246:249], v[124:127]
	global_load_lds_dwordx4 v137, s[6:7]
	ds_read_b128 v[176:179], v194 offset:38912
	v_mfma_f32_16x16x32_bf16 v[0:3], v[180:183], v[204:207], v[0:3]
	s_add_u32 s4, s4, 0x80
	s_addc_u32 s5, s5, 0
	s_add_u32 s6, s6, 0x80
	s_addc_u32 s7, s7, 0
	v_mfma_f32_16x16x32_bf16 v[4:7], v[180:183], v[222:225], v[4:7]
	v_mfma_f32_16x16x32_bf16 v[8:11], v[180:183], v[226:229], v[8:11]
	v_mfma_f32_16x16x32_bf16 v[12:15], v[180:183], v[230:233], v[12:15]
	v_mfma_f32_16x16x32_bf16 v[16:19], v[180:183], v[234:237], v[16:19]
	v_mfma_f32_16x16x32_bf16 v[20:23], v[180:183], v[238:241], v[20:23]
	v_mfma_f32_16x16x32_bf16 v[24:27], v[180:183], v[242:245], v[24:27]
	v_mfma_f32_16x16x32_bf16 v[28:31], v[180:183], v[246:249], v[28:31]
	ds_read_b128 v[180:183], v194 offset:40960
	v_mfma_f32_16x16x32_bf16 v[32:35], v[200:203], v[204:207], v[32:35]
	ds_read_b128 v[204:207], v195 offset:36864
	v_mfma_f32_16x16x32_bf16 v[36:39], v[200:203], v[222:225], v[36:39]
	ds_read_b128 v[222:225], v195 offset:38912
	v_mfma_f32_16x16x32_bf16 v[40:43], v[200:203], v[226:229], v[40:43]
	ds_read_b128 v[226:229], v195 offset:40960
	v_mfma_f32_16x16x32_bf16 v[44:47], v[200:203], v[230:233], v[44:47]
	ds_read_b128 v[230:233], v195 offset:43008
	v_mfma_f32_16x16x32_bf16 v[48:51], v[200:203], v[234:237], v[48:51]
	ds_read_b128 v[234:237], v195 offset:45056
	v_mfma_f32_16x16x32_bf16 v[52:55], v[200:203], v[238:241], v[52:55]
	ds_read_b128 v[238:241], v195 offset:47104
	v_mfma_f32_16x16x32_bf16 v[56:59], v[200:203], v[242:245], v[56:59]
	ds_read_b128 v[242:245], v195 offset:49152
	v_mfma_f32_16x16x32_bf16 v[60:63], v[200:203], v[246:249], v[60:63]
	ds_read_b128 v[246:249], v195 offset:51200
	ds_read_b128 v[200:203], v194 offset:43008
	s_waitcnt lgkmcnt(8)
	v_mfma_f32_16x16x32_bf16 v[64:67], v[160:163], v[204:207], v[64:67]
	s_waitcnt lgkmcnt(7)
	v_mfma_f32_16x16x32_bf16 v[68:71], v[160:163], v[222:225], v[68:71]
	s_waitcnt lgkmcnt(6)
	v_mfma_f32_16x16x32_bf16 v[72:75], v[160:163], v[226:229], v[72:75]
	v_mfma_f32_16x16x32_bf16 v[140:143], v[160:163], v[160:163], v[140:143]
	s_waitcnt lgkmcnt(5)
	v_mfma_f32_16x16x32_bf16 v[76:79], v[160:163], v[230:233], v[76:79]
	s_waitcnt lgkmcnt(4)
	v_mfma_f32_16x16x32_bf16 v[80:83], v[160:163], v[234:237], v[80:83]
	s_waitcnt lgkmcnt(3)
	v_mfma_f32_16x16x32_bf16 v[84:87], v[160:163], v[238:241], v[84:87]
	s_waitcnt lgkmcnt(2)
	v_mfma_f32_16x16x32_bf16 v[88:91], v[160:163], v[242:245], v[88:91]
	s_waitcnt lgkmcnt(1)
	v_mfma_f32_16x16x32_bf16 v[92:95], v[160:163], v[246:249], v[92:95]
	ds_read_b128 v[160:163], v215 offset:36864
	v_mfma_f32_16x16x32_bf16 v[96:99], v[176:179], v[204:207], v[96:99]
	v_mfma_f32_16x16x32_bf16 v[100:103], v[176:179], v[222:225], v[100:103]
	v_mfma_f32_16x16x32_bf16 v[104:107], v[176:179], v[226:229], v[104:107]
	v_mfma_f32_16x16x32_bf16 v[144:147], v[176:179], v[176:179], v[144:147]
	v_mfma_f32_16x16x32_bf16 v[108:111], v[176:179], v[230:233], v[108:111]
	v_mfma_f32_16x16x32_bf16 v[112:115], v[176:179], v[234:237], v[112:115]
	v_mfma_f32_16x16x32_bf16 v[116:119], v[176:179], v[238:241], v[116:119]
	v_mfma_f32_16x16x32_bf16 v[120:123], v[176:179], v[242:245], v[120:123]
	v_mfma_f32_16x16x32_bf16 v[124:127], v[176:179], v[246:249], v[124:127]
	ds_read_b128 v[176:179], v215 offset:38912
	v_mfma_f32_16x16x32_bf16 v[0:3], v[180:183], v[204:207], v[0:3]
	v_mfma_f32_16x16x32_bf16 v[4:7], v[180:183], v[222:225], v[4:7]
	v_mfma_f32_16x16x32_bf16 v[8:11], v[180:183], v[226:229], v[8:11]
	v_mfma_f32_16x16x32_bf16 v[148:151], v[180:183], v[180:183], v[148:151]
	v_mfma_f32_16x16x32_bf16 v[12:15], v[180:183], v[230:233], v[12:15]
	v_mfma_f32_16x16x32_bf16 v[16:19], v[180:183], v[234:237], v[16:19]
	v_mfma_f32_16x16x32_bf16 v[20:23], v[180:183], v[238:241], v[20:23]
	v_mfma_f32_16x16x32_bf16 v[24:27], v[180:183], v[242:245], v[24:27]
	v_mfma_f32_16x16x32_bf16 v[28:31], v[180:183], v[246:249], v[28:31]
	ds_read_b128 v[180:183], v215 offset:40960
	s_waitcnt lgkmcnt(3)
	v_mfma_f32_16x16x32_bf16 v[32:35], v[200:203], v[204:207], v[32:35]
	ds_read_b128 v[204:207], v197 offset:36864
	v_mfma_f32_16x16x32_bf16 v[36:39], v[200:203], v[222:225], v[36:39]
	ds_read_b128 v[222:225], v197 offset:38912
	v_mfma_f32_16x16x32_bf16 v[40:43], v[200:203], v[226:229], v[40:43]
	v_mfma_f32_16x16x32_bf16 v[152:155], v[200:203], v[200:203], v[152:155]
	ds_read_b128 v[226:229], v197 offset:40960
	v_mfma_f32_16x16x32_bf16 v[44:47], v[200:203], v[230:233], v[44:47]
	ds_read_b128 v[230:233], v197 offset:43008
	v_mfma_f32_16x16x32_bf16 v[48:51], v[200:203], v[234:237], v[48:51]
	ds_read_b128 v[234:237], v197 offset:45056
	v_mfma_f32_16x16x32_bf16 v[52:55], v[200:203], v[238:241], v[52:55]
	ds_read_b128 v[238:241], v197 offset:47104
	v_mfma_f32_16x16x32_bf16 v[56:59], v[200:203], v[242:245], v[56:59]
	ds_read_b128 v[242:245], v197 offset:49152
	v_mfma_f32_16x16x32_bf16 v[60:63], v[200:203], v[246:249], v[60:63]
	ds_read_b128 v[246:249], v197 offset:51200
	ds_read_b128 v[200:203], v215 offset:43008
	s_waitcnt lgkmcnt(8)
	v_mfma_f32_16x16x32_bf16 v[64:67], v[160:163], v[204:207], v[64:67]
	s_waitcnt lgkmcnt(7)
	v_mfma_f32_16x16x32_bf16 v[68:71], v[160:163], v[222:225], v[68:71]
	s_waitcnt lgkmcnt(6)
	v_mfma_f32_16x16x32_bf16 v[72:75], v[160:163], v[226:229], v[72:75]
	s_waitcnt lgkmcnt(5)
	v_mfma_f32_16x16x32_bf16 v[76:79], v[160:163], v[230:233], v[76:79]
	s_waitcnt lgkmcnt(4)
	v_mfma_f32_16x16x32_bf16 v[80:83], v[160:163], v[234:237], v[80:83]
	s_waitcnt lgkmcnt(3)
	v_mfma_f32_16x16x32_bf16 v[84:87], v[160:163], v[238:241], v[84:87]
	s_waitcnt lgkmcnt(2)
	v_mfma_f32_16x16x32_bf16 v[88:91], v[160:163], v[242:245], v[88:91]
	s_waitcnt lgkmcnt(1)
	v_mfma_f32_16x16x32_bf16 v[92:95], v[160:163], v[246:249], v[92:95]
	s_waitcnt vmcnt(0) lgkmcnt(0)
	s_barrier
; DI void lds_barrier() { asm volatile("s_waitcnt lgkmcnt(0)\n\ts_barrier" ::: "memory"); }
; #define G_LOAD(RA, RB, KT) { size_t as_ = astep, bs_ = bstep; asm volatile("" : "+s"(as_), "+s"(bs_)); \
;       _Pragma("unroll") for (int i = 0; i < 4; ++i) { RA[i] = *(const u32x4*)(Ag + i * as_ + (KT) * 64); RB[i] = *(const u32x4*)(Bg + i * bs_ + (KT) * 64); } }
; DI void gemm_run(const GemmCfg c, char* smem, float* const g_h, u16* const g_hb, float* const g_out, const int final_out) {
;     ...
;     G_LOAD(ra0, rb0, 0);
;     __syncthreads();
;     G_STORE(ra0, rb0, 0);
;     G_LOAD(ra0, rb0, 1);
;     lds_barrier();
;     int kt = 0;
;     for (; kt + 3 < nk; kt += 2) {
;       K_STEP(0, 1, kt + 2, true, true);
;       lds_barrier();
;       K_STEP(1, 0, kt + 3, true, true);
;       lds_barrier();
;     }
	s_add_u32 m0, s8, 0x9000
	ds_read_b128 v[160:163], v194
	v_mfma_f32_16x16x32_bf16 v[96:99], v[176:179], v[204:207], v[96:99]
	global_load_lds_dwordx4 v130, s[4:5]
	s_add_u32 m0, s8, 0x1b000
	v_mfma_f32_16x16x32_bf16 v[100:103], v[176:179], v[222:225], v[100:103]
	global_load_lds_dwordx4 v134, s[6:7]
	s_add_u32 m0, s8, 0x9400
	v_mfma_f32_16x16x32_bf16 v[104:107], v[176:179], v[226:229], v[104:107]
	global_load_lds_dwordx4 v131, s[4:5]
	s_add_u32 m0, s8, 0x1b400
	v_mfma_f32_16x16x32_bf16 v[108:111], v[176:179], v[230:233], v[108:111]
	global_load_lds_dwordx4 v135, s[6:7]
	s_add_u32 m0, s8, 0x9800
	v_mfma_f32_16x16x32_bf16 v[112:115], v[176:179], v[234:237], v[112:115]
	global_load_lds_dwordx4 v132, s[4:5]
	s_add_u32 m0, s8, 0x1b800
	v_mfma_f32_16x16x32_bf16 v[116:119], v[176:179], v[238:241], v[116:119]
	global_load_lds_dwordx4 v136, s[6:7]
	s_add_u32 m0, s8, 0x9c00
	v_mfma_f32_16x16x32_bf16 v[120:123], v[176:179], v[242:245], v[120:123]
	global_load_lds_dwordx4 v133, s[4:5]
	s_add_u32 m0, s8, 0x1bc00
	v_mfma_f32_16x16x32_bf16 v[124:127], v[176:179], v[246:249], v[124:127]
	global_load_lds_dwordx4 v137, s[6:7]
	ds_read_b128 v[176:179], v194 offset:2048
	v_mfma_f32_16x16x32_bf16 v[0:3], v[180:183], v[204:207], v[0:3]
	s_add_u32 s4, s4, 0x80
	s_addc_u32 s5, s5, 0
	s_add_u32 s6, s6, 0x80
	s_addc_u32 s7, s7, 0
	v_mfma_f32_16x16x32_bf16 v[4:7], v[180:183], v[222:225], v[4:7]
	v_mfma_f32_16x16x32_bf16 v[8:11], v[180:183], v[226:229], v[8:11]
	v_mfma_f32_16x16x32_bf16 v[12:15], v[180:183], v[230:233], v[12:15]
	v_mfma_f32_16x16x32_bf16 v[16:19], v[180:183], v[234:237], v[16:19]
	v_mfma_f32_16x16x32_bf16 v[20:23], v[180:183], v[238:241], v[20:23]
	v_mfma_f32_16x16x32_bf16 v[24:27], v[180:183], v[242:245], v[24:27]
	v_mfma_f32_16x16x32_bf16 v[28:31], v[180:183], v[246:249], v[28:31]
	ds_read_b128 v[180:183], v194 offset:4096
	v_mfma_f32_16x16x32_bf16 v[32:35], v[200:203], v[204:207], v[32:35]
	ds_read_b128 v[204:207], v195
	v_mfma_f32_16x16x32_bf16 v[36:39], v[200:203], v[222:225], v[36:39]
	ds_read_b128 v[222:225], v195 offset:2048
	v_mfma_f32_16x16x32_bf16 v[40:43], v[200:203], v[226:229], v[40:43]
	ds_read_b128 v[226:229], v195 offset:4096
	v_mfma_f32_16x16x32_bf16 v[44:47], v[200:203], v[230:233], v[44:47]
	ds_read_b128 v[230:233], v195 offset:6144
	v_mfma_f32_16x16x32_bf16 v[48:51], v[200:203], v[234:237], v[48:51]
	ds_read_b128 v[234:237], v195 offset:8192
	v_mfma_f32_16x16x32_bf16 v[52:55], v[200:203], v[238:241], v[52:55]
	ds_read_b128 v[238:241], v195 offset:10240
	v_mfma_f32_16x16x32_bf16 v[56:59], v[200:203], v[242:245], v[56:59]
	ds_read_b128 v[242:245], v195 offset:12288
	v_mfma_f32_16x16x32_bf16 v[60:63], v[200:203], v[246:249], v[60:63]
	ds_read_b128 v[246:249], v195 offset:14336
	ds_read_b128 v[200:203], v194 offset:6144
	s_add_i32 s1, s1, 2
	s_cmp_lt_i32 s1, s0
	s_cbranch_scc1 .LBB0_112
	s_waitcnt lgkmcnt(8)
	v_mfma_f32_16x16x32_bf16 v[64:67], v[160:163], v[204:207], v[64:67]
	s_waitcnt lgkmcnt(7)
	v_mfma_f32_16x16x32_bf16 v[68:71], v[160:163], v[222:225], v[68:71]
	s_waitcnt lgkmcnt(6)
	v_mfma_f32_16x16x32_bf16 v[72:75], v[160:163], v[226:229], v[72:75]
	v_mfma_f32_16x16x32_bf16 v[140:143], v[160:163], v[160:163], v[140:143]
	s_waitcnt lgkmcnt(5)
	v_mfma_f32_16x16x32_bf16 v[76:79], v[160:163], v[230:233], v[76:79]
	s_waitcnt lgkmcnt(4)
	v_mfma_f32_16x16x32_bf16 v[80:83], v[160:163], v[234:237], v[80:83]
	s_waitcnt lgkmcnt(3)
	v_mfma_f32_16x16x32_bf16 v[84:87], v[160:163], v[238:241], v[84:87]
	s_waitcnt lgkmcnt(2)
	v_mfma_f32_16x16x32_bf16 v[88:91], v[160:163], v[242:245], v[88:91]
	s_waitcnt lgkmcnt(1)
	v_mfma_f32_16x16x32_bf16 v[92:95], v[160:163], v[246:249], v[92:95]
	ds_read_b128 v[160:163], v215
	v_mfma_f32_16x16x32_bf16 v[96:99], v[176:179], v[204:207], v[96:99]
	v_mfma_f32_16x16x32_bf16 v[100:103], v[176:179], v[222:225], v[100:103]
	v_mfma_f32_16x16x32_bf16 v[104:107], v[176:179], v[226:229], v[104:107]
	v_mfma_f32_16x16x32_bf16 v[144:147], v[176:179], v[176:179], v[144:147]
	v_mfma_f32_16x16x32_bf16 v[108:111], v[176:179], v[230:233], v[108:111]
	v_mfma_f32_16x16x32_bf16 v[112:115], v[176:179], v[234:237], v[112:115]
	v_mfma_f32_16x16x32_bf16 v[116:119], v[176:179], v[238:241], v[116:119]
	v_mfma_f32_16x16x32_bf16 v[120:123], v[176:179], v[242:245], v[120:123]
	v_mfma_f32_16x16x32_bf16 v[124:127], v[176:179], v[246:249], v[124:127]
	ds_read_b128 v[176:179], v215 offset:2048
	v_mfma_f32_16x16x32_bf16 v[0:3], v[180:183], v[204:207], v[0:3]
	v_mfma_f32_16x16x32_bf16 v[4:7], v[180:183], v[222:225], v[4:7]
	v_mfma_f32_16x16x32_bf16 v[8:11], v[180:183], v[226:229], v[8:11]
	v_mfma_f32_16x16x32_bf16 v[148:151], v[180:183], v[180:183], v[148:151]
	v_mfma_f32_16x16x32_bf16 v[12:15], v[180:183], v[230:233], v[12:15]
	v_mfma_f32_16x16x32_bf16 v[16:19], v[180:183], v[234:237], v[16:19]
	v_mfma_f32_16x16x32_bf16 v[20:23], v[180:183], v[238:241], v[20:23]
	v_mfma_f32_16x16x32_bf16 v[24:27], v[180:183], v[242:245], v[24:27]
	v_mfma_f32_16x16x32_bf16 v[28:31], v[180:183], v[246:249], v[28:31]
	ds_read_b128 v[180:183], v215 offset:4096
	s_waitcnt lgkmcnt(3)
	v_mfma_f32_16x16x32_bf16 v[32:35], v[200:203], v[204:207], v[32:35]
	ds_read_b128 v[204:207], v197
	v_mfma_f32_16x16x32_bf16 v[36:39], v[200:203], v[222:225], v[36:39]
	ds_read_b128 v[222:225], v197 offset:2048
	v_mfma_f32_16x16x32_bf16 v[40:43], v[200:203], v[226:229], v[40:43]
	v_mfma_f32_16x16x32_bf16 v[152:155], v[200:203], v[200:203], v[152:155]
	ds_read_b128 v[226:229], v197 offset:4096
	v_mfma_f32_16x16x32_bf16 v[44:47], v[200:203], v[230:233], v[44:47]
	ds_read_b128 v[230:233], v197 offset:6144
	v_mfma_f32_16x16x32_bf16 v[48:51], v[200:203], v[234:237], v[48:51]
	ds_read_b128 v[234:237], v197 offset:8192
	v_mfma_f32_16x16x32_bf16 v[52:55], v[200:203], v[238:241], v[52:55]
	ds_read_b128 v[238:241], v197 offset:10240
	v_mfma_f32_16x16x32_bf16 v[56:59], v[200:203], v[242:245], v[56:59]
	ds_read_b128 v[242:245], v197 offset:12288
	v_mfma_f32_16x16x32_bf16 v[60:63], v[200:203], v[246:249], v[60:63]
	ds_read_b128 v[246:249], v197 offset:14336
	ds_read_b128 v[200:203], v215 offset:6144
	s_waitcnt lgkmcnt(8)
	v_mfma_f32_16x16x32_bf16 v[64:67], v[160:163], v[204:207], v[64:67]
	s_waitcnt lgkmcnt(7)
	v_mfma_f32_16x16x32_bf16 v[68:71], v[160:163], v[222:225], v[68:71]
	s_waitcnt lgkmcnt(6)
	v_mfma_f32_16x16x32_bf16 v[72:75], v[160:163], v[226:229], v[72:75]
	s_waitcnt lgkmcnt(5)
	v_mfma_f32_16x16x32_bf16 v[76:79], v[160:163], v[230:233], v[76:79]
	s_waitcnt lgkmcnt(4)
	v_mfma_f32_16x16x32_bf16 v[80:83], v[160:163], v[234:237], v[80:83]
	s_waitcnt lgkmcnt(3)
	v_mfma_f32_16x16x32_bf16 v[84:87], v[160:163], v[238:241], v[84:87]
	s_waitcnt lgkmcnt(2)
	v_mfma_f32_16x16x32_bf16 v[88:91], v[160:163], v[242:245], v[88:91]
	s_waitcnt lgkmcnt(1)
	v_mfma_f32_16x16x32_bf16 v[92:95], v[160:163], v[246:249], v[92:95]
	s_waitcnt vmcnt(0) lgkmcnt(0)
	s_barrier
; DI void lds_barrier() { asm volatile("s_waitcnt lgkmcnt(0)\n\ts_barrier" ::: "memory"); }
; DI void gemm_run(const GemmCfg c, char* smem, float* const g_h, u16* const g_hb, float* const g_out, const int final_out) {
;     ...
;     K_STEP(0, 1, 0, true, false);
;     lds_barrier();
;     K_STEP(1, 0, 0, false, false);
;     lds_barrier();
	ds_read_b128 v[160:163], v194 offset:36864
	v_mfma_f32_16x16x32_bf16 v[96:99], v[176:179], v[204:207], v[96:99]
	v_mfma_f32_16x16x32_bf16 v[100:103], v[176:179], v[222:225], v[100:103]
	v_mfma_f32_16x16x32_bf16 v[104:107], v[176:179], v[226:229], v[104:107]
	v_mfma_f32_16x16x32_bf16 v[108:111], v[176:179], v[230:233], v[108:111]
	v_mfma_f32_16x16x32_bf16 v[112:115], v[176:179], v[234:237], v[112:115]
	v_mfma_f32_16x16x32_bf16 v[116:119], v[176:179], v[238:241], v[116:119]
	v_mfma_f32_16x16x32_bf16 v[120:123], v[176:179], v[242:245], v[120:123]
	v_mfma_f32_16x16x32_bf16 v[124:127], v[176:179], v[246:249], v[124:127]
	ds_read_b128 v[176:179], v194 offset:38912
	v_mfma_f32_16x16x32_bf16 v[0:3], v[180:183], v[204:207], v[0:3]
	v_mfma_f32_16x16x32_bf16 v[4:7], v[180:183], v[222:225], v[4:7]
	v_mfma_f32_16x16x32_bf16 v[8:11], v[180:183], v[226:229], v[8:11]
	v_mfma_f32_16x16x32_bf16 v[12:15], v[180:183], v[230:233], v[12:15]
	v_mfma_f32_16x16x32_bf16 v[16:19], v[180:183], v[234:237], v[16:19]
	v_mfma_f32_16x16x32_bf16 v[20:23], v[180:183], v[238:241], v[20:23]
	v_mfma_f32_16x16x32_bf16 v[24:27], v[180:183], v[242:245], v[24:27]
	v_mfma_f32_16x16x32_bf16 v[28:31], v[180:183], v[246:249], v[28:31]
	ds_read_b128 v[180:183], v194 offset:40960
	v_mfma_f32_16x16x32_bf16 v[32:35], v[200:203], v[204:207], v[32:35]
	ds_read_b128 v[204:207], v195 offset:36864
	v_mfma_f32_16x16x32_bf16 v[36:39], v[200:203], v[222:225], v[36:39]
	ds_read_b128 v[222:225], v195 offset:38912
	v_mfma_f32_16x16x32_bf16 v[40:43], v[200:203], v[226:229], v[40:43]
	ds_read_b128 v[226:229], v195 offset:40960
	v_mfma_f32_16x16x32_bf16 v[44:47], v[200:203], v[230:233], v[44:47]
	ds_read_b128 v[230:233], v195 offset:43008
	v_mfma_f32_16x16x32_bf16 v[48:51], v[200:203], v[234:237], v[48:51]
	ds_read_b128 v[234:237], v195 offset:45056
	v_mfma_f32_16x16x32_bf16 v[52:55], v[200:203], v[238:241], v[52:55]
	ds_read_b128 v[238:241], v195 offset:47104
	v_mfma_f32_16x16x32_bf16 v[56:59], v[200:203], v[242:245], v[56:59]
	ds_read_b128 v[242:245], v195 offset:49152
	v_mfma_f32_16x16x32_bf16 v[60:63], v[200:203], v[246:249], v[60:63]
	ds_read_b128 v[246:249], v195 offset:51200
	ds_read_b128 v[200:203], v194 offset:43008
	s_waitcnt lgkmcnt(8)
	v_mfma_f32_16x16x32_bf16 v[64:67], v[160:163], v[204:207], v[64:67]
	s_waitcnt lgkmcnt(7)
	v_mfma_f32_16x16x32_bf16 v[68:71], v[160:163], v[222:225], v[68:71]
	s_waitcnt lgkmcnt(6)
	v_mfma_f32_16x16x32_bf16 v[72:75], v[160:163], v[226:229], v[72:75]
	v_mfma_f32_16x16x32_bf16 v[140:143], v[160:163], v[160:163], v[140:143]
	s_waitcnt lgkmcnt(5)
	v_mfma_f32_16x16x32_bf16 v[76:79], v[160:163], v[230:233], v[76:79]
	s_waitcnt lgkmcnt(4)
	v_mfma_f32_16x16x32_bf16 v[80:83], v[160:163], v[234:237], v[80:83]
	s_waitcnt lgkmcnt(3)
	v_mfma_f32_16x16x32_bf16 v[84:87], v[160:163], v[238:241], v[84:87]
	s_waitcnt lgkmcnt(2)
	v_mfma_f32_16x16x32_bf16 v[88:91], v[160:163], v[242:245], v[88:91]
	s_waitcnt lgkmcnt(1)
	v_mfma_f32_16x16x32_bf16 v[92:95], v[160:163], v[246:249], v[92:95]
	ds_read_b128 v[160:163], v215 offset:36864
	v_mfma_f32_16x16x32_bf16 v[96:99], v[176:179], v[204:207], v[96:99]
	v_mfma_f32_16x16x32_bf16 v[100:103], v[176:179], v[222:225], v[100:103]
	v_mfma_f32_16x16x32_bf16 v[104:107], v[176:179], v[226:229], v[104:107]
	v_mfma_f32_16x16x32_bf16 v[144:147], v[176:179], v[176:179], v[144:147]
	v_mfma_f32_16x16x32_bf16 v[108:111], v[176:179], v[230:233], v[108:111]
	v_mfma_f32_16x16x32_bf16 v[112:115], v[176:179], v[234:237], v[112:115]
	v_mfma_f32_16x16x32_bf16 v[116:119], v[176:179], v[238:241], v[116:119]
	v_mfma_f32_16x16x32_bf16 v[120:123], v[176:179], v[242:245], v[120:123]
	v_mfma_f32_16x16x32_bf16 v[124:127], v[176:179], v[246:249], v[124:127]
	ds_read_b128 v[176:179], v215 offset:38912
	v_mfma_f32_16x16x32_bf16 v[0:3], v[180:183], v[204:207], v[0:3]
	v_mfma_f32_16x16x32_bf16 v[4:7], v[180:183], v[222:225], v[4:7]
	v_mfma_f32_16x16x32_bf16 v[8:11], v[180:183], v[226:229], v[8:11]
	v_mfma_f32_16x16x32_bf16 v[148:151], v[180:183], v[180:183], v[148:151]
	v_mfma_f32_16x16x32_bf16 v[12:15], v[180:183], v[230:233], v[12:15]
	v_mfma_f32_16x16x32_bf16 v[16:19], v[180:183], v[234:237], v[16:19]
	v_mfma_f32_16x16x32_bf16 v[20:23], v[180:183], v[238:241], v[20:23]
	v_mfma_f32_16x16x32_bf16 v[24:27], v[180:183], v[242:245], v[24:27]
	v_mfma_f32_16x16x32_bf16 v[28:31], v[180:183], v[246:249], v[28:31]
	ds_read_b128 v[180:183], v215 offset:40960
	s_waitcnt lgkmcnt(3)
	v_mfma_f32_16x16x32_bf16 v[32:35], v[200:203], v[204:207], v[32:35]
	ds_read_b128 v[204:207], v197 offset:36864
	v_mfma_f32_16x16x32_bf16 v[36:39], v[200:203], v[222:225], v[36:39]
	ds_read_b128 v[222:225], v197 offset:38912
	v_mfma_f32_16x16x32_bf16 v[40:43], v[200:203], v[226:229], v[40:43]
	v_mfma_f32_16x16x32_bf16 v[152:155], v[200:203], v[200:203], v[152:155]
	ds_read_b128 v[226:229], v197 offset:40960
	v_mfma_f32_16x16x32_bf16 v[44:47], v[200:203], v[230:233], v[44:47]
	ds_read_b128 v[230:233], v197 offset:43008
	v_mfma_f32_16x16x32_bf16 v[48:51], v[200:203], v[234:237], v[48:51]
	ds_read_b128 v[234:237], v197 offset:45056
	v_mfma_f32_16x16x32_bf16 v[52:55], v[200:203], v[238:241], v[52:55]
	ds_read_b128 v[238:241], v197 offset:47104
	v_mfma_f32_16x16x32_bf16 v[56:59], v[200:203], v[242:245], v[56:59]
	ds_read_b128 v[242:245], v197 offset:49152
	v_mfma_f32_16x16x32_bf16 v[60:63], v[200:203], v[246:249], v[60:63]
	ds_read_b128 v[246:249], v197 offset:51200
	ds_read_b128 v[200:203], v215 offset:43008
	s_waitcnt lgkmcnt(8)
	v_mfma_f32_16x16x32_bf16 v[64:67], v[160:163], v[204:207], v[64:67]
	s_waitcnt lgkmcnt(7)
	v_mfma_f32_16x16x32_bf16 v[68:71], v[160:163], v[222:225], v[68:71]
	s_waitcnt lgkmcnt(6)
; DI void lds_barrier() { asm volatile("s_waitcnt lgkmcnt(0)\n\ts_barrier" ::: "memory"); }
; DI void gemm_run(const GemmCfg c, char* smem, float* const g_h, u16* const g_hb, float* const g_out, const int final_out) {
;     ...
;     K_STEP(0, 1, 0, true, false);
;     lds_barrier();
;     K_STEP(1, 0, 0, false, false);
;     lds_barrier();
	v_mfma_f32_16x16x32_bf16 v[72:75], v[160:163], v[226:229], v[72:75]
	s_waitcnt lgkmcnt(5)
	v_mfma_f32_16x16x32_bf16 v[76:79], v[160:163], v[230:233], v[76:79]
	s_waitcnt lgkmcnt(4)
	v_mfma_f32_16x16x32_bf16 v[80:83], v[160:163], v[234:237], v[80:83]
	s_waitcnt lgkmcnt(3)
	v_mfma_f32_16x16x32_bf16 v[84:87], v[160:163], v[238:241], v[84:87]
	s_waitcnt lgkmcnt(2)
	v_mfma_f32_16x16x32_bf16 v[88:91], v[160:163], v[242:245], v[88:91]
	s_waitcnt lgkmcnt(1)
	v_mfma_f32_16x16x32_bf16 v[92:95], v[160:163], v[246:249], v[92:95]
	v_mfma_f32_16x16x32_bf16 v[96:99], v[176:179], v[204:207], v[96:99]
	v_mfma_f32_16x16x32_bf16 v[100:103], v[176:179], v[222:225], v[100:103]
	v_mfma_f32_16x16x32_bf16 v[104:107], v[176:179], v[226:229], v[104:107]
	v_mfma_f32_16x16x32_bf16 v[108:111], v[176:179], v[230:233], v[108:111]
	v_mfma_f32_16x16x32_bf16 v[112:115], v[176:179], v[234:237], v[112:115]
	v_mfma_f32_16x16x32_bf16 v[116:119], v[176:179], v[238:241], v[116:119]
	v_mfma_f32_16x16x32_bf16 v[120:123], v[176:179], v[242:245], v[120:123]
	v_mfma_f32_16x16x32_bf16 v[124:127], v[176:179], v[246:249], v[124:127]
	v_mfma_f32_16x16x32_bf16 v[0:3], v[180:183], v[204:207], v[0:3]
	v_mfma_f32_16x16x32_bf16 v[4:7], v[180:183], v[222:225], v[4:7]
	v_mfma_f32_16x16x32_bf16 v[8:11], v[180:183], v[226:229], v[8:11]
	v_mfma_f32_16x16x32_bf16 v[12:15], v[180:183], v[230:233], v[12:15]
	v_mfma_f32_16x16x32_bf16 v[16:19], v[180:183], v[234:237], v[16:19]
	v_mfma_f32_16x16x32_bf16 v[20:23], v[180:183], v[238:241], v[20:23]
	v_mfma_f32_16x16x32_bf16 v[24:27], v[180:183], v[242:245], v[24:27]
	v_mfma_f32_16x16x32_bf16 v[28:31], v[180:183], v[246:249], v[28:31]
	s_waitcnt lgkmcnt(0)
	v_mfma_f32_16x16x32_bf16 v[32:35], v[200:203], v[204:207], v[32:35]
	v_mfma_f32_16x16x32_bf16 v[36:39], v[200:203], v[222:225], v[36:39]
	v_mfma_f32_16x16x32_bf16 v[40:43], v[200:203], v[226:229], v[40:43]
	v_mfma_f32_16x16x32_bf16 v[44:47], v[200:203], v[230:233], v[44:47]
	v_mfma_f32_16x16x32_bf16 v[48:51], v[200:203], v[234:237], v[48:51]
	v_mfma_f32_16x16x32_bf16 v[52:55], v[200:203], v[238:241], v[52:55]
	v_mfma_f32_16x16x32_bf16 v[56:59], v[200:203], v[242:245], v[56:59]
	v_mfma_f32_16x16x32_bf16 v[60:63], v[200:203], v[246:249], v[60:63]
	s_branch .Lgemm_kdone
.Lgemm_kloop_r1e:
	s_waitcnt lgkmcnt(8)
	v_mfma_f32_16x16x32_bf16 v[64:67], v[160:163], v[204:207], v[64:67]
	s_waitcnt lgkmcnt(7)
	v_mfma_f32_16x16x32_bf16 v[68:71], v[160:163], v[222:225], v[68:71]
	s_waitcnt lgkmcnt(6)
	v_mfma_f32_16x16x32_bf16 v[72:75], v[160:163], v[226:229], v[72:75]
	s_waitcnt lgkmcnt(5)
	v_mfma_f32_16x16x32_bf16 v[76:79], v[160:163], v[230:233], v[76:79]
	s_waitcnt lgkmcnt(4)
	v_mfma_f32_16x16x32_bf16 v[80:83], v[160:163], v[234:237], v[80:83]
	s_waitcnt lgkmcnt(3)
	v_mfma_f32_16x16x32_bf16 v[84:87], v[160:163], v[238:241], v[84:87]
	s_waitcnt lgkmcnt(2)
	v_mfma_f32_16x16x32_bf16 v[88:91], v[160:163], v[242:245], v[88:91]
	s_waitcnt lgkmcnt(1)
	v_mfma_f32_16x16x32_bf16 v[92:95], v[160:163], v[246:249], v[92:95]
	ds_read_b128 v[160:163], v215
	v_mfma_f32_16x16x32_bf16 v[96:99], v[176:179], v[204:207], v[96:99]
	v_mfma_f32_16x16x32_bf16 v[100:103], v[176:179], v[222:225], v[100:103]
	v_mfma_f32_16x16x32_bf16 v[104:107], v[176:179], v[226:229], v[104:107]
	v_mfma_f32_16x16x32_bf16 v[108:111], v[176:179], v[230:233], v[108:111]
	v_mfma_f32_16x16x32_bf16 v[112:115], v[176:179], v[234:237], v[112:115]
	v_mfma_f32_16x16x32_bf16 v[116:119], v[176:179], v[238:241], v[116:119]
	v_mfma_f32_16x16x32_bf16 v[120:123], v[176:179], v[242:245], v[120:123]
	v_mfma_f32_16x16x32_bf16 v[124:127], v[176:179], v[246:249], v[124:127]
	ds_read_b128 v[176:179], v215 offset:2048
	v_mfma_f32_16x16x32_bf16 v[0:3], v[180:183], v[204:207], v[0:3]
	v_mfma_f32_16x16x32_bf16 v[4:7], v[180:183], v[222:225], v[4:7]
	v_mfma_f32_16x16x32_bf16 v[8:11], v[180:183], v[226:229], v[8:11]
	v_mfma_f32_16x16x32_bf16 v[12:15], v[180:183], v[230:233], v[12:15]
	v_mfma_f32_16x16x32_bf16 v[16:19], v[180:183], v[234:237], v[16:19]
	v_mfma_f32_16x16x32_bf16 v[20:23], v[180:183], v[238:241], v[20:23]
	v_mfma_f32_16x16x32_bf16 v[24:27], v[180:183], v[242:245], v[24:27]
	v_mfma_f32_16x16x32_bf16 v[28:31], v[180:183], v[246:249], v[28:31]
	ds_read_b128 v[180:183], v215 offset:4096
	s_waitcnt lgkmcnt(3)
	v_mfma_f32_16x16x32_bf16 v[32:35], v[200:203], v[204:207], v[32:35]
	ds_read_b128 v[204:207], v197
	v_mfma_f32_16x16x32_bf16 v[36:39], v[200:203], v[222:225], v[36:39]
	ds_read_b128 v[222:225], v197 offset:2048
	v_mfma_f32_16x16x32_bf16 v[40:43], v[200:203], v[226:229], v[40:43]
	ds_read_b128 v[226:229], v197 offset:4096
	v_mfma_f32_16x16x32_bf16 v[44:47], v[200:203], v[230:233], v[44:47]
	ds_read_b128 v[230:233], v197 offset:6144
	v_mfma_f32_16x16x32_bf16 v[48:51], v[200:203], v[234:237], v[48:51]
	ds_read_b128 v[234:237], v197 offset:8192
	v_mfma_f32_16x16x32_bf16 v[52:55], v[200:203], v[238:241], v[52:55]
	ds_read_b128 v[238:241], v197 offset:10240
	v_mfma_f32_16x16x32_bf16 v[56:59], v[200:203], v[242:245], v[56:59]
	ds_read_b128 v[242:245], v197 offset:12288
	v_mfma_f32_16x16x32_bf16 v[60:63], v[200:203], v[246:249], v[60:63]
	ds_read_b128 v[246:249], v197 offset:14336
	ds_read_b128 v[200:203], v215 offset:6144
	s_waitcnt lgkmcnt(8)
	v_mfma_f32_16x16x32_bf16 v[64:67], v[160:163], v[204:207], v[64:67]
	s_waitcnt lgkmcnt(7)
	v_mfma_f32_16x16x32_bf16 v[68:71], v[160:163], v[222:225], v[68:71]
	s_waitcnt lgkmcnt(6)
	v_mfma_f32_16x16x32_bf16 v[72:75], v[160:163], v[226:229], v[72:75]
	v_mfma_f32_16x16x32_bf16 v[140:143], v[160:163], v[160:163], v[140:143]
	s_waitcnt lgkmcnt(5)
	v_mfma_f32_16x16x32_bf16 v[76:79], v[160:163], v[230:233], v[76:79]
	s_waitcnt lgkmcnt(4)
	v_mfma_f32_16x16x32_bf16 v[80:83], v[160:163], v[234:237], v[80:83]
	s_waitcnt lgkmcnt(3)
	v_mfma_f32_16x16x32_bf16 v[84:87], v[160:163], v[238:241], v[84:87]
	s_waitcnt lgkmcnt(2)
	v_mfma_f32_16x16x32_bf16 v[88:91], v[160:163], v[242:245], v[88:91]
	s_waitcnt lgkmcnt(1)
	v_mfma_f32_16x16x32_bf16 v[92:95], v[160:163], v[246:249], v[92:95]
	s_waitcnt vmcnt(0) lgkmcnt(0)
	s_barrier
; DI void lds_barrier() { asm volatile("s_waitcnt lgkmcnt(0)\n\ts_barrier" ::: "memory"); }
; #define G_LOAD(RA, RB, KT) { size_t as_ = astep, bs_ = bstep; asm volatile("" : "+s"(as_), "+s"(bs_)); \
;       _Pragma("unroll") for (int i = 0; i < 4; ++i) { RA[i] = *(const u32x4*)(Ag + i * as_ + (KT) * 64); RB[i] = *(const u32x4*)(Bg + i * bs_ + (KT) * 64); } }
; DI void gemm_run(const GemmCfg c, char* smem, float* const g_h, u16* const g_hb, float* const g_out, const int final_out) {
;     ...
;     G_LOAD(ra0, rb0, 0);
;     __syncthreads();
;     G_STORE(ra0, rb0, 0);
;     G_LOAD(ra0, rb0, 1);
;     lds_barrier();
;     int kt = 0;
;     for (; kt + 3 < nk; kt += 2) {
;       K_STEP(0, 1, kt + 2, true, true);
;       lds_barrier();
;       K_STEP(1, 0, kt + 3, true, true);
;       lds_barrier();
;     }
	s_add_u32 m0, s8, 0x0
	ds_read_b128 v[160:163], v194 offset:36864
	v_mfma_f32_16x16x32_bf16 v[96:99], v[176:179], v[204:207], v[96:99]
	global_load_lds_dwordx4 v130, s[4:5]
	s_add_u32 m0, s8, 0x12000
	v_mfma_f32_16x16x32_bf16 v[100:103], v[176:179], v[222:225], v[100:103]
	global_load_lds_dwordx4 v134, s[6:7]
	s_add_u32 m0, s8, 0x400
	v_mfma_f32_16x16x32_bf16 v[104:107], v[176:179], v[226:229], v[104:107]
	v_mfma_f32_16x16x32_bf16 v[144:147], v[176:179], v[176:179], v[144:147]
	global_load_lds_dwordx4 v131, s[4:5]
	s_add_u32 m0, s8, 0x12400
	v_mfma_f32_16x16x32_bf16 v[108:111], v[176:179], v[230:233], v[108:111]
	global_load_lds_dwordx4 v135, s[6:7]
	s_add_u32 m0, s8, 0x800
	v_mfma_f32_16x16x32_bf16 v[112:115], v[176:179], v[234:237], v[112:115]
	global_load_lds_dwordx4 v132, s[4:5]
	s_add_u32 m0, s8, 0x12800
	v_mfma_f32_16x16x32_bf16 v[116:119], v[176:179], v[238:241], v[116:119]
	global_load_lds_dwordx4 v136, s[6:7]
	s_add_u32 m0, s8, 0xc00
	v_mfma_f32_16x16x32_bf16 v[120:123], v[176:179], v[242:245], v[120:123]
	global_load_lds_dwordx4 v133, s[4:5]
	s_add_u32 m0, s8, 0x12c00
	v_mfma_f32_16x16x32_bf16 v[124:127], v[176:179], v[246:249], v[124:127]
	global_load_lds_dwordx4 v137, s[6:7]
	ds_read_b128 v[176:179], v194 offset:38912
	v_mfma_f32_16x16x32_bf16 v[0:3], v[180:183], v[204:207], v[0:3]
	s_add_u32 s4, s4, 0x80
	s_addc_u32 s5, s5, 0
	s_add_u32 s6, s6, 0x80
	s_addc_u32 s7, s7, 0
	v_mfma_f32_16x16x32_bf16 v[4:7], v[180:183], v[222:225], v[4:7]
	v_mfma_f32_16x16x32_bf16 v[8:11], v[180:183], v[226:229], v[8:11]
	v_mfma_f32_16x16x32_bf16 v[148:151], v[180:183], v[180:183], v[148:151]
	v_mfma_f32_16x16x32_bf16 v[12:15], v[180:183], v[230:233], v[12:15]
	v_mfma_f32_16x16x32_bf16 v[16:19], v[180:183], v[234:237], v[16:19]
	v_mfma_f32_16x16x32_bf16 v[20:23], v[180:183], v[238:241], v[20:23]
	v_mfma_f32_16x16x32_bf16 v[24:27], v[180:183], v[242:245], v[24:27]
	v_mfma_f32_16x16x32_bf16 v[28:31], v[180:183], v[246:249], v[28:31]
	ds_read_b128 v[180:183], v194 offset:40960
	v_mfma_f32_16x16x32_bf16 v[32:35], v[200:203], v[204:207], v[32:35]
	ds_read_b128 v[204:207], v195 offset:36864
	v_mfma_f32_16x16x32_bf16 v[36:39], v[200:203], v[222:225], v[36:39]
	ds_read_b128 v[222:225], v195 offset:38912
	v_mfma_f32_16x16x32_bf16 v[40:43], v[200:203], v[226:229], v[40:43]
	v_mfma_f32_16x16x32_bf16 v[152:155], v[200:203], v[200:203], v[152:155]
	ds_read_b128 v[226:229], v195 offset:40960
	v_mfma_f32_16x16x32_bf16 v[44:47], v[200:203], v[230:233], v[44:47]
	ds_read_b128 v[230:233], v195 offset:43008
	v_mfma_f32_16x16x32_bf16 v[48:51], v[200:203], v[234:237], v[48:51]
	ds_read_b128 v[234:237], v195 offset:45056
	v_mfma_f32_16x16x32_bf16 v[52:55], v[200:203], v[238:241], v[52:55]
	ds_read_b128 v[238:241], v195 offset:47104
	v_mfma_f32_16x16x32_bf16 v[56:59], v[200:203], v[242:245], v[56:59]
	ds_read_b128 v[242:245], v195 offset:49152
	v_mfma_f32_16x16x32_bf16 v[60:63], v[200:203], v[246:249], v[60:63]
	ds_read_b128 v[246:249], v195 offset:51200
	ds_read_b128 v[200:203], v194 offset:43008
	s_waitcnt lgkmcnt(8)
	v_mfma_f32_16x16x32_bf16 v[64:67], v[160:163], v[204:207], v[64:67]
	s_waitcnt lgkmcnt(7)
	v_mfma_f32_16x16x32_bf16 v[68:71], v[160:163], v[222:225], v[68:71]
	s_waitcnt lgkmcnt(6)
	v_mfma_f32_16x16x32_bf16 v[72:75], v[160:163], v[226:229], v[72:75]
	s_waitcnt lgkmcnt(5)
	v_mfma_f32_16x16x32_bf16 v[76:79], v[160:163], v[230:233], v[76:79]
	s_waitcnt lgkmcnt(4)
	v_mfma_f32_16x16x32_bf16 v[80:83], v[160:163], v[234:237], v[80:83]
	s_waitcnt lgkmcnt(3)
	v_mfma_f32_16x16x32_bf16 v[84:87], v[160:163], v[238:241], v[84:87]
	s_waitcnt lgkmcnt(2)
	v_mfma_f32_16x16x32_bf16 v[88:91], v[160:163], v[242:245], v[88:91]
	s_waitcnt lgkmcnt(1)
	v_mfma_f32_16x16x32_bf16 v[92:95], v[160:163], v[246:249], v[92:95]
	ds_read_b128 v[160:163], v215 offset:36864
	v_mfma_f32_16x16x32_bf16 v[96:99], v[176:179], v[204:207], v[96:99]
	v_mfma_f32_16x16x32_bf16 v[100:103], v[176:179], v[222:225], v[100:103]
	v_mfma_f32_16x16x32_bf16 v[104:107], v[176:179], v[226:229], v[104:107]
	v_mfma_f32_16x16x32_bf16 v[108:111], v[176:179], v[230:233], v[108:111]
	v_mfma_f32_16x16x32_bf16 v[112:115], v[176:179], v[234:237], v[112:115]
	v_mfma_f32_16x16x32_bf16 v[116:119], v[176:179], v[238:241], v[116:119]
	v_mfma_f32_16x16x32_bf16 v[120:123], v[176:179], v[242:245], v[120:123]
	v_mfma_f32_16x16x32_bf16 v[124:127], v[176:179], v[246:249], v[124:127]
	ds_read_b128 v[176:179], v215 offset:38912
	v_mfma_f32_16x16x32_bf16 v[0:3], v[180:183], v[204:207], v[0:3]
	v_mfma_f32_16x16x32_bf16 v[4:7], v[180:183], v[222:225], v[4:7]
	v_mfma_f32_16x16x32_bf16 v[8:11], v[180:183], v[226:229], v[8:11]
	v_mfma_f32_16x16x32_bf16 v[12:15], v[180:183], v[230:233], v[12:15]
	v_mfma_f32_16x16x32_bf16 v[16:19], v[180:183], v[234:237], v[16:19]
	v_mfma_f32_16x16x32_bf16 v[20:23], v[180:183], v[238:241], v[20:23]
	v_mfma_f32_16x16x32_bf16 v[24:27], v[180:183], v[242:245], v[24:27]
	v_mfma_f32_16x16x32_bf16 v[28:31], v[180:183], v[246:249], v[28:31]
	ds_read_b128 v[180:183], v215 offset:40960
	s_waitcnt lgkmcnt(3)
	v_mfma_f32_16x16x32_bf16 v[32:35], v[200:203], v[204:207], v[32:35]
	ds_read_b128 v[204:207], v197 offset:36864
	v_mfma_f32_16x16x32_bf16 v[36:39], v[200:203], v[222:225], v[36:39]
	ds_read_b128 v[222:225], v197 offset:38912
	v_mfma_f32_16x16x32_bf16 v[40:43], v[200:203], v[226:229], v[40:43]
	ds_read_b128 v[226:229], v197 offset:40960
	v_mfma_f32_16x16x32_bf16 v[44:47], v[200:203], v[230:233], v[44:47]
	ds_read_b128 v[230:233], v197 offset:43008
	v_mfma_f32_16x16x32_bf16 v[48:51], v[200:203], v[234:237], v[48:51]
	ds_read_b128 v[234:237], v197 offset:45056
	v_mfma_f32_16x16x32_bf16 v[52:55], v[200:203], v[238:241], v[52:55]
	ds_read_b128 v[238:241], v197 offset:47104
	v_mfma_f32_16x16x32_bf16 v[56:59], v[200:203], v[242:245], v[56:59]
	ds_read_b128 v[242:245], v197 offset:49152
	v_mfma_f32_16x16x32_bf16 v[60:63], v[200:203], v[246:249], v[60:63]
	ds_read_b128 v[246:249], v197 offset:51200
	ds_read_b128 v[200:203], v215 offset:43008
	s_waitcnt lgkmcnt(8)
	v_mfma_f32_16x16x32_bf16 v[64:67], v[160:163], v[204:207], v[64:67]
	s_waitcnt lgkmcnt(7)
	v_mfma_f32_16x16x32_bf16 v[68:71], v[160:163], v[222:225], v[68:71]
	s_waitcnt lgkmcnt(6)
	v_mfma_f32_16x16x32_bf16 v[72:75], v[160:163], v[226:229], v[72:75]
	v_mfma_f32_16x16x32_bf16 v[140:143], v[160:163], v[160:163], v[140:143]
	s_waitcnt lgkmcnt(5)
	v_mfma_f32_16x16x32_bf16 v[76:79], v[160:163], v[230:233], v[76:79]
	s_waitcnt lgkmcnt(4)
	v_mfma_f32_16x16x32_bf16 v[80:83], v[160:163], v[234:237], v[80:83]
	s_waitcnt lgkmcnt(3)
	v_mfma_f32_16x16x32_bf16 v[84:87], v[160:163], v[238:241], v[84:87]
	s_waitcnt lgkmcnt(2)
	v_mfma_f32_16x16x32_bf16 v[88:91], v[160:163], v[242:245], v[88:91]
	s_waitcnt lgkmcnt(1)
	v_mfma_f32_16x16x32_bf16 v[92:95], v[160:163], v[246:249], v[92:95]
	s_waitcnt vmcnt(0) lgkmcnt(0)
	s_barrier
; DI void lds_barrier() { asm volatile("s_waitcnt lgkmcnt(0)\n\ts_barrier" ::: "memory"); }
; #define G_LOAD(RA, RB, KT) { size_t as_ = astep, bs_ = bstep; asm volatile("" : "+s"(as_), "+s"(bs_)); \
;       _Pragma("unroll") for (int i = 0; i < 4; ++i) { RA[i] = *(const u32x4*)(Ag + i * as_ + (KT) * 64); RB[i] = *(const u32x4*)(Bg + i * bs_ + (KT) * 64); } }
; DI void gemm_run(const GemmCfg c, char* smem, float* const g_h, u16* const g_hb, float* const g_out, const int final_out) {
;     ...
;     G_LOAD(ra0, rb0, 0);
;     __syncthreads();
;     G_STORE(ra0, rb0, 0);
;     G_LOAD(ra0, rb0, 1);
;     lds_barrier();
;     int kt = 0;
;     for (; kt + 3 < nk; kt += 2) {
;       K_STEP(0, 1, kt + 2, true, true);
;       lds_barrier();
;       K_STEP(1, 0, kt + 3, true, true);
;       lds_barrier();
;     }
	s_add_u32 m0, s8, 0x9000
	ds_read_b128 v[160:163], v194
	v_mfma_f32_16x16x32_bf16 v[96:99], v[176:179], v[204:207], v[96:99]
	global_load_lds_dwordx4 v130, s[4:5]
	s_add_u32 m0, s8, 0x1b000
	v_mfma_f32_16x16x32_bf16 v[100:103], v[176:179], v[222:225], v[100:103]
	global_load_lds_dwordx4 v134, s[6:7]
	s_add_u32 m0, s8, 0x9400
	v_mfma_f32_16x16x32_bf16 v[104:107], v[176:179], v[226:229], v[104:107]
	v_mfma_f32_16x16x32_bf16 v[144:147], v[176:179], v[176:179], v[144:147]
	global_load_lds_dwordx4 v131, s[4:5]
	s_add_u32 m0, s8, 0x1b400
	v_mfma_f32_16x16x32_bf16 v[108:111], v[176:179], v[230:233], v[108:111]
	global_load_lds_dwordx4 v135, s[6:7]
	s_add_u32 m0, s8, 0x9800
	v_mfma_f32_16x16x32_bf16 v[112:115], v[176:179], v[234:237], v[112:115]
	global_load_lds_dwordx4 v132, s[4:5]
	s_add_u32 m0, s8, 0x1b800
	v_mfma_f32_16x16x32_bf16 v[116:119], v[176:179], v[238:241], v[116:119]
	global_load_lds_dwordx4 v136, s[6:7]
	s_add_u32 m0, s8, 0x9c00
	v_mfma_f32_16x16x32_bf16 v[120:123], v[176:179], v[242:245], v[120:123]
	global_load_lds_dwordx4 v133, s[4:5]
	s_add_u32 m0, s8, 0x1bc00
	v_mfma_f32_16x16x32_bf16 v[124:127], v[176:179], v[246:249], v[124:127]
	global_load_lds_dwordx4 v137, s[6:7]
	ds_read_b128 v[176:179], v194 offset:2048
	v_mfma_f32_16x16x32_bf16 v[0:3], v[180:183], v[204:207], v[0:3]
	s_add_u32 s4, s4, 0x80
	s_addc_u32 s5, s5, 0
	s_add_u32 s6, s6, 0x80
	s_addc_u32 s7, s7, 0
	v_mfma_f32_16x16x32_bf16 v[4:7], v[180:183], v[222:225], v[4:7]
	v_mfma_f32_16x16x32_bf16 v[8:11], v[180:183], v[226:229], v[8:11]
	v_mfma_f32_16x16x32_bf16 v[148:151], v[180:183], v[180:183], v[148:151]
	v_mfma_f32_16x16x32_bf16 v[12:15], v[180:183], v[230:233], v[12:15]
	v_mfma_f32_16x16x32_bf16 v[16:19], v[180:183], v[234:237], v[16:19]
	v_mfma_f32_16x16x32_bf16 v[20:23], v[180:183], v[238:241], v[20:23]
	v_mfma_f32_16x16x32_bf16 v[24:27], v[180:183], v[242:245], v[24:27]
	v_mfma_f32_16x16x32_bf16 v[28:31], v[180:183], v[246:249], v[28:31]
	ds_read_b128 v[180:183], v194 offset:4096
	v_mfma_f32_16x16x32_bf16 v[32:35], v[200:203], v[204:207], v[32:35]
	ds_read_b128 v[204:207], v195
	v_mfma_f32_16x16x32_bf16 v[36:39], v[200:203], v[222:225], v[36:39]
	ds_read_b128 v[222:225], v195 offset:2048
	v_mfma_f32_16x16x32_bf16 v[40:43], v[200:203], v[226:229], v[40:43]
	v_mfma_f32_16x16x32_bf16 v[152:155], v[200:203], v[200:203], v[152:155]
	ds_read_b128 v[226:229], v195 offset:4096
	v_mfma_f32_16x16x32_bf16 v[44:47], v[200:203], v[230:233], v[44:47]
	ds_read_b128 v[230:233], v195 offset:6144
	v_mfma_f32_16x16x32_bf16 v[48:51], v[200:203], v[234:237], v[48:51]
	ds_read_b128 v[234:237], v195 offset:8192
	v_mfma_f32_16x16x32_bf16 v[52:55], v[200:203], v[238:241], v[52:55]
	ds_read_b128 v[238:241], v195 offset:10240
	v_mfma_f32_16x16x32_bf16 v[56:59], v[200:203], v[242:245], v[56:59]
	ds_read_b128 v[242:245], v195 offset:12288
	v_mfma_f32_16x16x32_bf16 v[60:63], v[200:203], v[246:249], v[60:63]
	ds_read_b128 v[246:249], v195 offset:14336
	ds_read_b128 v[200:203], v194 offset:6144
	s_add_i32 s1, s1, 2
	s_cmp_lt_i32 s1, s0
	s_cbranch_scc1 .Lgemm_kloop_r1e
	s_waitcnt lgkmcnt(8)
	v_mfma_f32_16x16x32_bf16 v[64:67], v[160:163], v[204:207], v[64:67]
	s_waitcnt lgkmcnt(7)
	v_mfma_f32_16x16x32_bf16 v[68:71], v[160:163], v[222:225], v[68:71]
	s_waitcnt lgkmcnt(6)
	v_mfma_f32_16x16x32_bf16 v[72:75], v[160:163], v[226:229], v[72:75]
	s_waitcnt lgkmcnt(5)
	v_mfma_f32_16x16x32_bf16 v[76:79], v[160:163], v[230:233], v[76:79]
	s_waitcnt lgkmcnt(4)
	v_mfma_f32_16x16x32_bf16 v[80:83], v[160:163], v[234:237], v[80:83]
	s_waitcnt lgkmcnt(3)
	v_mfma_f32_16x16x32_bf16 v[84:87], v[160:163], v[238:241], v[84:87]
	s_waitcnt lgkmcnt(2)
	v_mfma_f32_16x16x32_bf16 v[88:91], v[160:163], v[242:245], v[88:91]
	s_waitcnt lgkmcnt(1)
	v_mfma_f32_16x16x32_bf16 v[92:95], v[160:163], v[246:249], v[92:95]
	ds_read_b128 v[160:163], v215
	v_mfma_f32_16x16x32_bf16 v[96:99], v[176:179], v[204:207], v[96:99]
	v_mfma_f32_16x16x32_bf16 v[100:103], v[176:179], v[222:225], v[100:103]
	v_mfma_f32_16x16x32_bf16 v[104:107], v[176:179], v[226:229], v[104:107]
	v_mfma_f32_16x16x32_bf16 v[108:111], v[176:179], v[230:233], v[108:111]
	v_mfma_f32_16x16x32_bf16 v[112:115], v[176:179], v[234:237], v[112:115]
	v_mfma_f32_16x16x32_bf16 v[116:119], v[176:179], v[238:241], v[116:119]
	v_mfma_f32_16x16x32_bf16 v[120:123], v[176:179], v[242:245], v[120:123]
	v_mfma_f32_16x16x32_bf16 v[124:127], v[176:179], v[246:249], v[124:127]
	ds_read_b128 v[176:179], v215 offset:2048
	v_mfma_f32_16x16x32_bf16 v[0:3], v[180:183], v[204:207], v[0:3]
	v_mfma_f32_16x16x32_bf16 v[4:7], v[180:183], v[222:225], v[4:7]
	v_mfma_f32_16x16x32_bf16 v[8:11], v[180:183], v[226:229], v[8:11]
	v_mfma_f32_16x16x32_bf16 v[12:15], v[180:183], v[230:233], v[12:15]
	v_mfma_f32_16x16x32_bf16 v[16:19], v[180:183], v[234:237], v[16:19]
	v_mfma_f32_16x16x32_bf16 v[20:23], v[180:183], v[238:241], v[20:23]
	v_mfma_f32_16x16x32_bf16 v[24:27], v[180:183], v[242:245], v[24:27]
	v_mfma_f32_16x16x32_bf16 v[28:31], v[180:183], v[246:249], v[28:31]
	ds_read_b128 v[180:183], v215 offset:4096
	s_waitcnt lgkmcnt(3)
	v_mfma_f32_16x16x32_bf16 v[32:35], v[200:203], v[204:207], v[32:35]
	ds_read_b128 v[204:207], v197
	v_mfma_f32_16x16x32_bf16 v[36:39], v[200:203], v[222:225], v[36:39]
	ds_read_b128 v[222:225], v197 offset:2048
	v_mfma_f32_16x16x32_bf16 v[40:43], v[200:203], v[226:229], v[40:43]
	ds_read_b128 v[226:229], v197 offset:4096
	v_mfma_f32_16x16x32_bf16 v[44:47], v[200:203], v[230:233], v[44:47]
	ds_read_b128 v[230:233], v197 offset:6144
	v_mfma_f32_16x16x32_bf16 v[48:51], v[200:203], v[234:237], v[48:51]
	ds_read_b128 v[234:237], v197 offset:8192
	v_mfma_f32_16x16x32_bf16 v[52:55], v[200:203], v[238:241], v[52:55]
	ds_read_b128 v[238:241], v197 offset:10240
	v_mfma_f32_16x16x32_bf16 v[56:59], v[200:203], v[242:245], v[56:59]
	ds_read_b128 v[242:245], v197 offset:12288
	v_mfma_f32_16x16x32_bf16 v[60:63], v[200:203], v[246:249], v[60:63]
	ds_read_b128 v[246:249], v197 offset:14336
	ds_read_b128 v[200:203], v215 offset:6144
	s_waitcnt lgkmcnt(8)
	v_mfma_f32_16x16x32_bf16 v[64:67], v[160:163], v[204:207], v[64:67]
	s_waitcnt lgkmcnt(7)
	v_mfma_f32_16x16x32_bf16 v[68:71], v[160:163], v[222:225], v[68:71]
	s_waitcnt lgkmcnt(6)
	v_mfma_f32_16x16x32_bf16 v[72:75], v[160:163], v[226:229], v[72:75]
	v_mfma_f32_16x16x32_bf16 v[140:143], v[160:163], v[160:163], v[140:143]
	s_waitcnt lgkmcnt(5)
	v_mfma_f32_16x16x32_bf16 v[76:79], v[160:163], v[230:233], v[76:79]
	s_waitcnt lgkmcnt(4)
	v_mfma_f32_16x16x32_bf16 v[80:83], v[160:163], v[234:237], v[80:83]
	s_waitcnt lgkmcnt(3)
	v_mfma_f32_16x16x32_bf16 v[84:87], v[160:163], v[238:241], v[84:87]
	s_waitcnt lgkmcnt(2)
	v_mfma_f32_16x16x32_bf16 v[88:91], v[160:163], v[242:245], v[88:91]
	s_waitcnt lgkmcnt(1)
	v_mfma_f32_16x16x32_bf16 v[92:95], v[160:163], v[246:249], v[92:95]
	s_waitcnt vmcnt(0) lgkmcnt(0)
	s_barrier
; DI void lds_barrier() { asm volatile("s_waitcnt lgkmcnt(0)\n\ts_barrier" ::: "memory"); }
; DI void gemm_run(const GemmCfg c, char* smem, float* const g_h, u16* const g_hb, float* const g_out, const int final_out) {
;     ...
;     K_STEP(0, 1, 0, true, false);
;     lds_barrier();
;     K_STEP(1, 0, 0, false, false);
;     lds_barrier();
	ds_read_b128 v[160:163], v194 offset:36864
	v_mfma_f32_16x16x32_bf16 v[96:99], v[176:179], v[204:207], v[96:99]
	v_mfma_f32_16x16x32_bf16 v[100:103], v[176:179], v[222:225], v[100:103]
	v_mfma_f32_16x16x32_bf16 v[104:107], v[176:179], v[226:229], v[104:107]
	v_mfma_f32_16x16x32_bf16 v[144:147], v[176:179], v[176:179], v[144:147]
	v_mfma_f32_16x16x32_bf16 v[108:111], v[176:179], v[230:233], v[108:111]
	v_mfma_f32_16x16x32_bf16 v[112:115], v[176:179], v[234:237], v[112:115]
	v_mfma_f32_16x16x32_bf16 v[116:119], v[176:179], v[238:241], v[116:119]
	v_mfma_f32_16x16x32_bf16 v[120:123], v[176:179], v[242:245], v[120:123]
	v_mfma_f32_16x16x32_bf16 v[124:127], v[176:179], v[246:249], v[124:127]
	ds_read_b128 v[176:179], v194 offset:38912
	v_mfma_f32_16x16x32_bf16 v[0:3], v[180:183], v[204:207], v[0:3]
	v_mfma_f32_16x16x32_bf16 v[4:7], v[180:183], v[222:225], v[4:7]
	v_mfma_f32_16x16x32_bf16 v[8:11], v[180:183], v[226:229], v[8:11]
	v_mfma_f32_16x16x32_bf16 v[148:151], v[180:183], v[180:183], v[148:151]
	v_mfma_f32_16x16x32_bf16 v[12:15], v[180:183], v[230:233], v[12:15]
	v_mfma_f32_16x16x32_bf16 v[16:19], v[180:183], v[234:237], v[16:19]
	v_mfma_f32_16x16x32_bf16 v[20:23], v[180:183], v[238:241], v[20:23]
	v_mfma_f32_16x16x32_bf16 v[24:27], v[180:183], v[242:245], v[24:27]
	v_mfma_f32_16x16x32_bf16 v[28:31], v[180:183], v[246:249], v[28:31]
	ds_read_b128 v[180:183], v194 offset:40960
	v_mfma_f32_16x16x32_bf16 v[32:35], v[200:203], v[204:207], v[32:35]
	ds_read_b128 v[204:207], v195 offset:36864
	v_mfma_f32_16x16x32_bf16 v[36:39], v[200:203], v[222:225], v[36:39]
	ds_read_b128 v[222:225], v195 offset:38912
	v_mfma_f32_16x16x32_bf16 v[40:43], v[200:203], v[226:229], v[40:43]
	v_mfma_f32_16x16x32_bf16 v[152:155], v[200:203], v[200:203], v[152:155]
	ds_read_b128 v[226:229], v195 offset:40960
	v_mfma_f32_16x16x32_bf16 v[44:47], v[200:203], v[230:233], v[44:47]
	ds_read_b128 v[230:233], v195 offset:43008
	v_mfma_f32_16x16x32_bf16 v[48:51], v[200:203], v[234:237], v[48:51]
	ds_read_b128 v[234:237], v195 offset:45056
	v_mfma_f32_16x16x32_bf16 v[52:55], v[200:203], v[238:241], v[52:55]
	ds_read_b128 v[238:241], v195 offset:47104
	v_mfma_f32_16x16x32_bf16 v[56:59], v[200:203], v[242:245], v[56:59]
	ds_read_b128 v[242:245], v195 offset:49152
	v_mfma_f32_16x16x32_bf16 v[60:63], v[200:203], v[246:249], v[60:63]
	ds_read_b128 v[246:249], v195 offset:51200
	ds_read_b128 v[200:203], v194 offset:43008
	s_waitcnt lgkmcnt(8)
	v_mfma_f32_16x16x32_bf16 v[64:67], v[160:163], v[204:207], v[64:67]
	s_waitcnt lgkmcnt(7)
	v_mfma_f32_16x16x32_bf16 v[68:71], v[160:163], v[222:225], v[68:71]
	s_waitcnt lgkmcnt(6)
	v_mfma_f32_16x16x32_bf16 v[72:75], v[160:163], v[226:229], v[72:75]
	s_waitcnt lgkmcnt(5)
	v_mfma_f32_16x16x32_bf16 v[76:79], v[160:163], v[230:233], v[76:79]
	s_waitcnt lgkmcnt(4)
	v_mfma_f32_16x16x32_bf16 v[80:83], v[160:163], v[234:237], v[80:83]
	s_waitcnt lgkmcnt(3)
	v_mfma_f32_16x16x32_bf16 v[84:87], v[160:163], v[238:241], v[84:87]
	s_waitcnt lgkmcnt(2)
	v_mfma_f32_16x16x32_bf16 v[88:91], v[160:163], v[242:245], v[88:91]
	s_waitcnt lgkmcnt(1)
	v_mfma_f32_16x16x32_bf16 v[92:95], v[160:163], v[246:249], v[92:95]
	ds_read_b128 v[160:163], v215 offset:36864
	v_mfma_f32_16x16x32_bf16 v[96:99], v[176:179], v[204:207], v[96:99]
	v_mfma_f32_16x16x32_bf16 v[100:103], v[176:179], v[222:225], v[100:103]
	v_mfma_f32_16x16x32_bf16 v[104:107], v[176:179], v[226:229], v[104:107]
	v_mfma_f32_16x16x32_bf16 v[108:111], v[176:179], v[230:233], v[108:111]
	v_mfma_f32_16x16x32_bf16 v[112:115], v[176:179], v[234:237], v[112:115]
	v_mfma_f32_16x16x32_bf16 v[116:119], v[176:179], v[238:241], v[116:119]
	v_mfma_f32_16x16x32_bf16 v[120:123], v[176:179], v[242:245], v[120:123]
	v_mfma_f32_16x16x32_bf16 v[124:127], v[176:179], v[246:249], v[124:127]
	ds_read_b128 v[176:179], v215 offset:38912
	v_mfma_f32_16x16x32_bf16 v[0:3], v[180:183], v[204:207], v[0:3]
	v_mfma_f32_16x16x32_bf16 v[4:7], v[180:183], v[222:225], v[4:7]
	v_mfma_f32_16x16x32_bf16 v[8:11], v[180:183], v[226:229], v[8:11]
	v_mfma_f32_16x16x32_bf16 v[12:15], v[180:183], v[230:233], v[12:15]
	v_mfma_f32_16x16x32_bf16 v[16:19], v[180:183], v[234:237], v[16:19]
	v_mfma_f32_16x16x32_bf16 v[20:23], v[180:183], v[238:241], v[20:23]
	v_mfma_f32_16x16x32_bf16 v[24:27], v[180:183], v[242:245], v[24:27]
	v_mfma_f32_16x16x32_bf16 v[28:31], v[180:183], v[246:249], v[28:31]
	ds_read_b128 v[180:183], v215 offset:40960
	s_waitcnt lgkmcnt(3)
	v_mfma_f32_16x16x32_bf16 v[32:35], v[200:203], v[204:207], v[32:35]
	ds_read_b128 v[204:207], v197 offset:36864
	v_mfma_f32_16x16x32_bf16 v[36:39], v[200:203], v[222:225], v[36:39]
	ds_read_b128 v[222:225], v197 offset:38912
	v_mfma_f32_16x16x32_bf16 v[40:43], v[200:203], v[226:229], v[40:43]
	ds_read_b128 v[226:229], v197 offset:40960
	v_mfma_f32_16x16x32_bf16 v[44:47], v[200:203], v[230:233], v[44:47]
	ds_read_b128 v[230:233], v197 offset:43008
	v_mfma_f32_16x16x32_bf16 v[48:51], v[200:203], v[234:237], v[48:51]
	ds_read_b128 v[234:237], v197 offset:45056
	v_mfma_f32_16x16x32_bf16 v[52:55], v[200:203], v[238:241], v[52:55]
	ds_read_b128 v[238:241], v197 offset:47104
	v_mfma_f32_16x16x32_bf16 v[56:59], v[200:203], v[242:245], v[56:59]
	ds_read_b128 v[242:245], v197 offset:49152
	v_mfma_f32_16x16x32_bf16 v[60:63], v[200:203], v[246:249], v[60:63]
	ds_read_b128 v[246:249], v197 offset:51200
	ds_read_b128 v[200:203], v215 offset:43008
	s_waitcnt lgkmcnt(8)
	v_mfma_f32_16x16x32_bf16 v[64:67], v[160:163], v[204:207], v[64:67]
	s_waitcnt lgkmcnt(7)
	v_mfma_f32_16x16x32_bf16 v[68:71], v[160:163], v[222:225], v[68:71]
	s_waitcnt lgkmcnt(6)
; DI void lds_barrier() { asm volatile("s_waitcnt lgkmcnt(0)\n\ts_barrier" ::: "memory"); }
; #define G_LOAD(RA, RB, KT) { size_t as_ = astep, bs_ = bstep; asm volatile("" : "+s"(as_), "+s"(bs_)); \
;       _Pragma("unroll") for (int i = 0; i < 4; ++i) { RA[i] = *(const u32x4*)(Ag + i * as_ + (KT) * 64); RB[i] = *(const u32x4*)(Bg + i * bs_ + (KT) * 64); } }
; DI void gemm_run(const GemmCfg c, char* smem, float* const g_h, u16* const g_hb, float* const g_out, const int final_out) {
;     ...
;     G_LOAD(ra0, rb0, 0);
;     __syncthreads();
;     G_STORE(ra0, rb0, 0);
;     G_LOAD(ra0, rb0, 1);
;     lds_barrier();
;     int kt = 0;
;     for (; kt + 3 < nk; kt += 2) {
;       K_STEP(0, 1, kt + 2, true, true);
;       lds_barrier();
;       K_STEP(1, 0, kt + 3, true, true);
;       lds_barrier();
;     }
	v_mfma_f32_16x16x32_bf16 v[72:75], v[160:163], v[226:229], v[72:75]
	v_mfma_f32_16x16x32_bf16 v[140:143], v[160:163], v[160:163], v[140:143]
	s_waitcnt lgkmcnt(5)
	v_mfma_f32_16x16x32_bf16 v[76:79], v[160:163], v[230:233], v[76:79]
	s_waitcnt lgkmcnt(4)
	v_mfma_f32_16x16x32_bf16 v[80:83], v[160:163], v[234:237], v[80:83]
	s_waitcnt lgkmcnt(3)
	v_mfma_f32_16x16x32_bf16 v[84:87], v[160:163], v[238:241], v[84:87]
	s_waitcnt lgkmcnt(2)
	v_mfma_f32_16x16x32_bf16 v[88:91], v[160:163], v[242:245], v[88:91]
	s_waitcnt lgkmcnt(1)
	v_mfma_f32_16x16x32_bf16 v[92:95], v[160:163], v[246:249], v[92:95]
	v_mfma_f32_16x16x32_bf16 v[96:99], v[176:179], v[204:207], v[96:99]
	v_mfma_f32_16x16x32_bf16 v[100:103], v[176:179], v[222:225], v[100:103]
	v_mfma_f32_16x16x32_bf16 v[104:107], v[176:179], v[226:229], v[104:107]
	v_mfma_f32_16x16x32_bf16 v[144:147], v[176:179], v[176:179], v[144:147]
	v_mfma_f32_16x16x32_bf16 v[108:111], v[176:179], v[230:233], v[108:111]
	v_mfma_f32_16x16x32_bf16 v[112:115], v[176:179], v[234:237], v[112:115]
	v_mfma_f32_16x16x32_bf16 v[116:119], v[176:179], v[238:241], v[116:119]
	v_mfma_f32_16x16x32_bf16 v[120:123], v[176:179], v[242:245], v[120:123]
	v_mfma_f32_16x16x32_bf16 v[124:127], v[176:179], v[246:249], v[124:127]
	v_mfma_f32_16x16x32_bf16 v[0:3], v[180:183], v[204:207], v[0:3]
	v_mfma_f32_16x16x32_bf16 v[4:7], v[180:183], v[222:225], v[4:7]
	v_mfma_f32_16x16x32_bf16 v[8:11], v[180:183], v[226:229], v[8:11]
	v_mfma_f32_16x16x32_bf16 v[148:151], v[180:183], v[180:183], v[148:151]
	v_mfma_f32_16x16x32_bf16 v[12:15], v[180:183], v[230:233], v[12:15]
	v_mfma_f32_16x16x32_bf16 v[16:19], v[180:183], v[234:237], v[16:19]
	v_mfma_f32_16x16x32_bf16 v[20:23], v[180:183], v[238:241], v[20:23]
	v_mfma_f32_16x16x32_bf16 v[24:27], v[180:183], v[242:245], v[24:27]
	v_mfma_f32_16x16x32_bf16 v[28:31], v[180:183], v[246:249], v[28:31]
	s_waitcnt lgkmcnt(0)
	v_mfma_f32_16x16x32_bf16 v[32:35], v[200:203], v[204:207], v[32:35]
	v_mfma_f32_16x16x32_bf16 v[36:39], v[200:203], v[222:225], v[36:39]
	v_mfma_f32_16x16x32_bf16 v[40:43], v[200:203], v[226:229], v[40:43]
	v_mfma_f32_16x16x32_bf16 v[152:155], v[200:203], v[200:203], v[152:155]
	v_mfma_f32_16x16x32_bf16 v[44:47], v[200:203], v[230:233], v[44:47]
	v_mfma_f32_16x16x32_bf16 v[48:51], v[200:203], v[234:237], v[48:51]
	v_mfma_f32_16x16x32_bf16 v[52:55], v[200:203], v[238:241], v[52:55]
	v_mfma_f32_16x16x32_bf16 v[56:59], v[200:203], v[242:245], v[56:59]
	v_mfma_f32_16x16x32_bf16 v[60:63], v[200:203], v[246:249], v[60:63]
	s_branch .Lgemm_kdone
.Lgemm_kloop_rl:
	s_waitcnt lgkmcnt(8)
	v_mfma_f32_16x16x32_bf16 v[64:67], v[160:163], v[204:207], v[64:67]
	s_waitcnt lgkmcnt(7)
	v_mfma_f32_16x16x32_bf16 v[68:71], v[160:163], v[222:225], v[68:71]
	s_waitcnt lgkmcnt(6)
	v_mfma_f32_16x16x32_bf16 v[72:75], v[160:163], v[226:229], v[72:75]
	v_mfma_f32_16x16x32_bf16 v[140:143], v[160:163], v[160:163], v[140:143]
	s_waitcnt lgkmcnt(5)
	v_mfma_f32_16x16x32_bf16 v[76:79], v[160:163], v[230:233], v[76:79]
	s_waitcnt lgkmcnt(4)
	v_mfma_f32_16x16x32_bf16 v[80:83], v[160:163], v[234:237], v[80:83]
	s_waitcnt lgkmcnt(3)
	v_mfma_f32_16x16x32_bf16 v[84:87], v[160:163], v[238:241], v[84:87]
	s_waitcnt lgkmcnt(2)
	v_mfma_f32_16x16x32_bf16 v[88:91], v[160:163], v[242:245], v[88:91]
	s_waitcnt lgkmcnt(1)
	v_mfma_f32_16x16x32_bf16 v[92:95], v[160:163], v[246:249], v[92:95]
	ds_read_b128 v[160:163], v215
	v_mfma_f32_16x16x32_bf16 v[96:99], v[176:179], v[204:207], v[96:99]
	v_mfma_f32_16x16x32_bf16 v[100:103], v[176:179], v[222:225], v[100:103]
	v_mfma_f32_16x16x32_bf16 v[104:107], v[176:179], v[226:229], v[104:107]
	v_mfma_f32_16x16x32_bf16 v[144:147], v[176:179], v[176:179], v[144:147]
	v_mfma_f32_16x16x32_bf16 v[108:111], v[176:179], v[230:233], v[108:111]
	v_mfma_f32_16x16x32_bf16 v[112:115], v[176:179], v[234:237], v[112:115]
	v_mfma_f32_16x16x32_bf16 v[116:119], v[176:179], v[238:241], v[116:119]
	v_mfma_f32_16x16x32_bf16 v[120:123], v[176:179], v[242:245], v[120:123]
	v_mfma_f32_16x16x32_bf16 v[124:127], v[176:179], v[246:249], v[124:127]
	ds_read_b128 v[176:179], v215 offset:2048
	v_mfma_f32_16x16x32_bf16 v[0:3], v[180:183], v[204:207], v[0:3]
	v_mfma_f32_16x16x32_bf16 v[4:7], v[180:183], v[222:225], v[4:7]
	v_mfma_f32_16x16x32_bf16 v[8:11], v[180:183], v[226:229], v[8:11]
	v_mfma_f32_16x16x32_bf16 v[148:151], v[180:183], v[180:183], v[148:151]
	v_mfma_f32_16x16x32_bf16 v[12:15], v[180:183], v[230:233], v[12:15]
	v_mfma_f32_16x16x32_bf16 v[16:19], v[180:183], v[234:237], v[16:19]
	v_mfma_f32_16x16x32_bf16 v[20:23], v[180:183], v[238:241], v[20:23]
	v_mfma_f32_16x16x32_bf16 v[24:27], v[180:183], v[242:245], v[24:27]
	v_mfma_f32_16x16x32_bf16 v[28:31], v[180:183], v[246:249], v[28:31]
	ds_read_b128 v[180:183], v215 offset:4096
	s_waitcnt lgkmcnt(3)
	v_mfma_f32_16x16x32_bf16 v[32:35], v[200:203], v[204:207], v[32:35]
	ds_read_b128 v[204:207], v197
	v_mfma_f32_16x16x32_bf16 v[36:39], v[200:203], v[222:225], v[36:39]
	ds_read_b128 v[222:225], v197 offset:2048
	v_mfma_f32_16x16x32_bf16 v[40:43], v[200:203], v[226:229], v[40:43]
	v_mfma_f32_16x16x32_bf16 v[152:155], v[200:203], v[200:203], v[152:155]
	ds_read_b128 v[226:229], v197 offset:4096
	v_mfma_f32_16x16x32_bf16 v[44:47], v[200:203], v[230:233], v[44:47]
	ds_read_b128 v[230:233], v197 offset:6144
	v_mfma_f32_16x16x32_bf16 v[48:51], v[200:203], v[234:237], v[48:51]
	ds_read_b128 v[234:237], v197 offset:8192
	v_mfma_f32_16x16x32_bf16 v[52:55], v[200:203], v[238:241], v[52:55]
	ds_read_b128 v[238:241], v197 offset:10240
	v_mfma_f32_16x16x32_bf16 v[56:59], v[200:203], v[242:245], v[56:59]
	ds_read_b128 v[242:245], v197 offset:12288
	v_mfma_f32_16x16x32_bf16 v[60:63], v[200:203], v[246:249], v[60:63]
	ds_read_b128 v[246:249], v197 offset:14336
	ds_read_b128 v[200:203], v215 offset:6144
	s_waitcnt lgkmcnt(8)
	v_mfma_f32_16x16x32_bf16 v[64:67], v[160:163], v[204:207], v[64:67]
	s_waitcnt lgkmcnt(7)
	v_mfma_f32_16x16x32_bf16 v[68:71], v[160:163], v[222:225], v[68:71]
	s_waitcnt lgkmcnt(6)
	v_mfma_f32_16x16x32_bf16 v[72:75], v[160:163], v[226:229], v[72:75]
	s_waitcnt lgkmcnt(5)
	v_mfma_f32_16x16x32_bf16 v[76:79], v[160:163], v[230:233], v[76:79]
	s_waitcnt lgkmcnt(4)
	v_mfma_f32_16x16x32_bf16 v[80:83], v[160:163], v[234:237], v[80:83]
	s_waitcnt lgkmcnt(3)
	v_mfma_f32_16x16x32_bf16 v[84:87], v[160:163], v[238:241], v[84:87]
	s_waitcnt lgkmcnt(2)
	v_mfma_f32_16x16x32_bf16 v[88:91], v[160:163], v[242:245], v[88:91]
	s_waitcnt lgkmcnt(1)
	v_mfma_f32_16x16x32_bf16 v[92:95], v[160:163], v[246:249], v[92:95]
	s_waitcnt vmcnt(0) lgkmcnt(0)
	s_barrier
; DI void lds_barrier() { asm volatile("s_waitcnt lgkmcnt(0)\n\ts_barrier" ::: "memory"); }
; #define G_LOAD(RA, RB, KT) { size_t as_ = astep, bs_ = bstep; asm volatile("" : "+s"(as_), "+s"(bs_)); \
;       _Pragma("unroll") for (int i = 0; i < 4; ++i) { RA[i] = *(const u32x4*)(Ag + i * as_ + (KT) * 64); RB[i] = *(const u32x4*)(Bg + i * bs_ + (KT) * 64); } }
; DI void gemm_run(const GemmCfg c, char* smem, float* const g_h, u16* const g_hb, float* const g_out, const int final_out) {
;     ...
;     G_LOAD(ra0, rb0, 0);
;     __syncthreads();
;     G_STORE(ra0, rb0, 0);
;     G_LOAD(ra0, rb0, 1);
;     lds_barrier();
;     int kt = 0;
;     for (; kt + 3 < nk; kt += 2) {
;       K_STEP(0, 1, kt + 2, true, true);
;       lds_barrier();
;       K_STEP(1, 0, kt + 3, true, true);
;       lds_barrier();
;     }
	ds_read_b128 v[160:163], v194 offset:36864
	v_mfma_f32_16x16x32_bf16 v[96:99], v[176:179], v[204:207], v[96:99]
	v_mfma_f32_16x16x32_bf16 v[100:103], v[176:179], v[222:225], v[100:103]
	v_mfma_f32_16x16x32_bf16 v[104:107], v[176:179], v[226:229], v[104:107]
	v_mfma_f32_16x16x32_bf16 v[108:111], v[176:179], v[230:233], v[108:111]
	v_mfma_f32_16x16x32_bf16 v[112:115], v[176:179], v[234:237], v[112:115]
	v_mfma_f32_16x16x32_bf16 v[116:119], v[176:179], v[238:241], v[116:119]
	v_mfma_f32_16x16x32_bf16 v[120:123], v[176:179], v[242:245], v[120:123]
	v_mfma_f32_16x16x32_bf16 v[124:127], v[176:179], v[246:249], v[124:127]
	s_add_u32 m0, s8, 0x0
	ds_read_b128 v[176:179], v194 offset:38912
	v_mfma_f32_16x16x32_bf16 v[0:3], v[180:183], v[204:207], v[0:3]
	global_load_lds_dwordx4 v130, s[4:5]
	s_add_u32 m0, s8, 0x12000
	v_mfma_f32_16x16x32_bf16 v[4:7], v[180:183], v[222:225], v[4:7]
	global_load_lds_dwordx4 v134, s[6:7]
	s_add_u32 m0, s8, 0x400
	v_mfma_f32_16x16x32_bf16 v[8:11], v[180:183], v[226:229], v[8:11]
	global_load_lds_dwordx4 v131, s[4:5]
	s_add_u32 m0, s8, 0x12400
	v_mfma_f32_16x16x32_bf16 v[12:15], v[180:183], v[230:233], v[12:15]
	global_load_lds_dwordx4 v135, s[6:7]
	s_add_u32 m0, s8, 0x800
	v_mfma_f32_16x16x32_bf16 v[16:19], v[180:183], v[234:237], v[16:19]
	global_load_lds_dwordx4 v132, s[4:5]
	s_add_u32 m0, s8, 0x12800
	v_mfma_f32_16x16x32_bf16 v[20:23], v[180:183], v[238:241], v[20:23]
	global_load_lds_dwordx4 v136, s[6:7]
	s_add_u32 m0, s8, 0xc00
	v_mfma_f32_16x16x32_bf16 v[24:27], v[180:183], v[242:245], v[24:27]
	global_load_lds_dwordx4 v133, s[4:5]
	s_add_u32 m0, s8, 0x12c00
	v_mfma_f32_16x16x32_bf16 v[28:31], v[180:183], v[246:249], v[28:31]
	global_load_lds_dwordx4 v137, s[6:7]
	ds_read_b128 v[180:183], v194 offset:40960
	v_mfma_f32_16x16x32_bf16 v[32:35], v[200:203], v[204:207], v[32:35]
	s_add_u32 s4, s4, 0x80
	s_addc_u32 s5, s5, 0
	s_add_u32 s6, s6, 0x80
	s_addc_u32 s7, s7, 0
	ds_read_b128 v[204:207], v195 offset:36864
	v_mfma_f32_16x16x32_bf16 v[36:39], v[200:203], v[222:225], v[36:39]
	ds_read_b128 v[222:225], v195 offset:38912
	v_mfma_f32_16x16x32_bf16 v[40:43], v[200:203], v[226:229], v[40:43]
	ds_read_b128 v[226:229], v195 offset:40960
	v_mfma_f32_16x16x32_bf16 v[44:47], v[200:203], v[230:233], v[44:47]
	ds_read_b128 v[230:233], v195 offset:43008
	v_mfma_f32_16x16x32_bf16 v[48:51], v[200:203], v[234:237], v[48:51]
	ds_read_b128 v[234:237], v195 offset:45056
	v_mfma_f32_16x16x32_bf16 v[52:55], v[200:203], v[238:241], v[52:55]
	ds_read_b128 v[238:241], v195 offset:47104
	v_mfma_f32_16x16x32_bf16 v[56:59], v[200:203], v[242:245], v[56:59]
	ds_read_b128 v[242:245], v195 offset:49152
	v_mfma_f32_16x16x32_bf16 v[60:63], v[200:203], v[246:249], v[60:63]
	ds_read_b128 v[246:249], v195 offset:51200
	ds_read_b128 v[200:203], v194 offset:43008
	s_waitcnt lgkmcnt(8)
	v_mfma_f32_16x16x32_bf16 v[64:67], v[160:163], v[204:207], v[64:67]
	s_waitcnt lgkmcnt(7)
	v_mfma_f32_16x16x32_bf16 v[68:71], v[160:163], v[222:225], v[68:71]
	s_waitcnt lgkmcnt(6)
	v_mfma_f32_16x16x32_bf16 v[72:75], v[160:163], v[226:229], v[72:75]
	v_mfma_f32_16x16x32_bf16 v[140:143], v[160:163], v[160:163], v[140:143]
	s_waitcnt lgkmcnt(5)
	v_mfma_f32_16x16x32_bf16 v[76:79], v[160:163], v[230:233], v[76:79]
	s_waitcnt lgkmcnt(4)
	v_mfma_f32_16x16x32_bf16 v[80:83], v[160:163], v[234:237], v[80:83]
	s_waitcnt lgkmcnt(3)
	v_mfma_f32_16x16x32_bf16 v[84:87], v[160:163], v[238:241], v[84:87]
	s_waitcnt lgkmcnt(2)
	v_mfma_f32_16x16x32_bf16 v[88:91], v[160:163], v[242:245], v[88:91]
	s_waitcnt lgkmcnt(1)
	v_mfma_f32_16x16x32_bf16 v[92:95], v[160:163], v[246:249], v[92:95]
	ds_read_b128 v[160:163], v215 offset:36864
	v_mfma_f32_16x16x32_bf16 v[96:99], v[176:179], v[204:207], v[96:99]
	v_mfma_f32_16x16x32_bf16 v[100:103], v[176:179], v[222:225], v[100:103]
	v_mfma_f32_16x16x32_bf16 v[104:107], v[176:179], v[226:229], v[104:107]
	v_mfma_f32_16x16x32_bf16 v[144:147], v[176:179], v[176:179], v[144:147]
	v_mfma_f32_16x16x32_bf16 v[108:111], v[176:179], v[230:233], v[108:111]
	v_mfma_f32_16x16x32_bf16 v[112:115], v[176:179], v[234:237], v[112:115]
	v_mfma_f32_16x16x32_bf16 v[116:119], v[176:179], v[238:241], v[116:119]
	v_mfma_f32_16x16x32_bf16 v[120:123], v[176:179], v[242:245], v[120:123]
	v_mfma_f32_16x16x32_bf16 v[124:127], v[176:179], v[246:249], v[124:127]
	ds_read_b128 v[176:179], v215 offset:38912
	v_mfma_f32_16x16x32_bf16 v[0:3], v[180:183], v[204:207], v[0:3]
	v_mfma_f32_16x16x32_bf16 v[4:7], v[180:183], v[222:225], v[4:7]
	v_mfma_f32_16x16x32_bf16 v[8:11], v[180:183], v[226:229], v[8:11]
	v_mfma_f32_16x16x32_bf16 v[148:151], v[180:183], v[180:183], v[148:151]
	v_mfma_f32_16x16x32_bf16 v[12:15], v[180:183], v[230:233], v[12:15]
	v_mfma_f32_16x16x32_bf16 v[16:19], v[180:183], v[234:237], v[16:19]
	v_mfma_f32_16x16x32_bf16 v[20:23], v[180:183], v[238:241], v[20:23]
	v_mfma_f32_16x16x32_bf16 v[24:27], v[180:183], v[242:245], v[24:27]
	v_mfma_f32_16x16x32_bf16 v[28:31], v[180:183], v[246:249], v[28:31]
	ds_read_b128 v[180:183], v215 offset:40960
	s_waitcnt lgkmcnt(3)
	v_mfma_f32_16x16x32_bf16 v[32:35], v[200:203], v[204:207], v[32:35]
	ds_read_b128 v[204:207], v197 offset:36864
	v_mfma_f32_16x16x32_bf16 v[36:39], v[200:203], v[222:225], v[36:39]
	ds_read_b128 v[222:225], v197 offset:38912
	v_mfma_f32_16x16x32_bf16 v[40:43], v[200:203], v[226:229], v[40:43]
	v_mfma_f32_16x16x32_bf16 v[152:155], v[200:203], v[200:203], v[152:155]
	ds_read_b128 v[226:229], v197 offset:40960
	v_mfma_f32_16x16x32_bf16 v[44:47], v[200:203], v[230:233], v[44:47]
	ds_read_b128 v[230:233], v197 offset:43008
	v_mfma_f32_16x16x32_bf16 v[48:51], v[200:203], v[234:237], v[48:51]
	ds_read_b128 v[234:237], v197 offset:45056
	v_mfma_f32_16x16x32_bf16 v[52:55], v[200:203], v[238:241], v[52:55]
	ds_read_b128 v[238:241], v197 offset:47104
	v_mfma_f32_16x16x32_bf16 v[56:59], v[200:203], v[242:245], v[56:59]
	ds_read_b128 v[242:245], v197 offset:49152
	v_mfma_f32_16x16x32_bf16 v[60:63], v[200:203], v[246:249], v[60:63]
	ds_read_b128 v[246:249], v197 offset:51200
	ds_read_b128 v[200:203], v215 offset:43008
	s_waitcnt lgkmcnt(8)
	v_mfma_f32_16x16x32_bf16 v[64:67], v[160:163], v[204:207], v[64:67]
	s_waitcnt lgkmcnt(7)
	v_mfma_f32_16x16x32_bf16 v[68:71], v[160:163], v[222:225], v[68:71]
	s_waitcnt lgkmcnt(6)
	v_mfma_f32_16x16x32_bf16 v[72:75], v[160:163], v[226:229], v[72:75]
	s_waitcnt lgkmcnt(5)
	v_mfma_f32_16x16x32_bf16 v[76:79], v[160:163], v[230:233], v[76:79]
	s_waitcnt lgkmcnt(4)
	v_mfma_f32_16x16x32_bf16 v[80:83], v[160:163], v[234:237], v[80:83]
	s_waitcnt lgkmcnt(3)
	v_mfma_f32_16x16x32_bf16 v[84:87], v[160:163], v[238:241], v[84:87]
	s_waitcnt lgkmcnt(2)
	v_mfma_f32_16x16x32_bf16 v[88:91], v[160:163], v[242:245], v[88:91]
	s_waitcnt lgkmcnt(1)
	v_mfma_f32_16x16x32_bf16 v[92:95], v[160:163], v[246:249], v[92:95]
	s_waitcnt vmcnt(0) lgkmcnt(0)
	s_barrier
; DI void lds_barrier() { asm volatile("s_waitcnt lgkmcnt(0)\n\ts_barrier" ::: "memory"); }
; #define G_LOAD(RA, RB, KT) { size_t as_ = astep, bs_ = bstep; asm volatile("" : "+s"(as_), "+s"(bs_)); \
;       _Pragma("unroll") for (int i = 0; i < 4; ++i) { RA[i] = *(const u32x4*)(Ag + i * as_ + (KT) * 64); RB[i] = *(const u32x4*)(Bg + i * bs_ + (KT) * 64); } }
; DI void gemm_run(const GemmCfg c, char* smem, float* const g_h, u16* const g_hb, float* const g_out, const int final_out) {
;     ...
;     G_LOAD(ra0, rb0, 0);
;     __syncthreads();
;     G_STORE(ra0, rb0, 0);
;     G_LOAD(ra0, rb0, 1);
;     lds_barrier();
;     int kt = 0;
;     for (; kt + 3 < nk; kt += 2) {
;       K_STEP(0, 1, kt + 2, true, true);
;       lds_barrier();
;       K_STEP(1, 0, kt + 3, true, true);
;       lds_barrier();
;     }
	ds_read_b128 v[160:163], v194
	v_mfma_f32_16x16x32_bf16 v[96:99], v[176:179], v[204:207], v[96:99]
	v_mfma_f32_16x16x32_bf16 v[100:103], v[176:179], v[222:225], v[100:103]
	v_mfma_f32_16x16x32_bf16 v[104:107], v[176:179], v[226:229], v[104:107]
	v_mfma_f32_16x16x32_bf16 v[108:111], v[176:179], v[230:233], v[108:111]
	v_mfma_f32_16x16x32_bf16 v[112:115], v[176:179], v[234:237], v[112:115]
	v_mfma_f32_16x16x32_bf16 v[116:119], v[176:179], v[238:241], v[116:119]
	v_mfma_f32_16x16x32_bf16 v[120:123], v[176:179], v[242:245], v[120:123]
	v_mfma_f32_16x16x32_bf16 v[124:127], v[176:179], v[246:249], v[124:127]
	s_add_u32 m0, s8, 0x9000
	ds_read_b128 v[176:179], v194 offset:2048
	v_mfma_f32_16x16x32_bf16 v[0:3], v[180:183], v[204:207], v[0:3]
	global_load_lds_dwordx4 v130, s[4:5]
	s_add_u32 m0, s8, 0x1b000
	v_mfma_f32_16x16x32_bf16 v[4:7], v[180:183], v[222:225], v[4:7]
	global_load_lds_dwordx4 v134, s[6:7]
	s_add_u32 m0, s8, 0x9400
	v_mfma_f32_16x16x32_bf16 v[8:11], v[180:183], v[226:229], v[8:11]
	global_load_lds_dwordx4 v131, s[4:5]
	s_add_u32 m0, s8, 0x1b400
	v_mfma_f32_16x16x32_bf16 v[12:15], v[180:183], v[230:233], v[12:15]
	global_load_lds_dwordx4 v135, s[6:7]
	s_add_u32 m0, s8, 0x9800
	v_mfma_f32_16x16x32_bf16 v[16:19], v[180:183], v[234:237], v[16:19]
	global_load_lds_dwordx4 v132, s[4:5]
	s_add_u32 m0, s8, 0x1b800
	v_mfma_f32_16x16x32_bf16 v[20:23], v[180:183], v[238:241], v[20:23]
	global_load_lds_dwordx4 v136, s[6:7]
	s_add_u32 m0, s8, 0x9c00
	v_mfma_f32_16x16x32_bf16 v[24:27], v[180:183], v[242:245], v[24:27]
	global_load_lds_dwordx4 v133, s[4:5]
	s_add_u32 m0, s8, 0x1bc00
	v_mfma_f32_16x16x32_bf16 v[28:31], v[180:183], v[246:249], v[28:31]
	global_load_lds_dwordx4 v137, s[6:7]
	ds_read_b128 v[180:183], v194 offset:4096
	v_mfma_f32_16x16x32_bf16 v[32:35], v[200:203], v[204:207], v[32:35]
	s_add_u32 s4, s4, 0x80
	s_addc_u32 s5, s5, 0
	s_add_u32 s6, s6, 0x80
	s_addc_u32 s7, s7, 0
	ds_read_b128 v[204:207], v195
	v_mfma_f32_16x16x32_bf16 v[36:39], v[200:203], v[222:225], v[36:39]
	ds_read_b128 v[222:225], v195 offset:2048
	v_mfma_f32_16x16x32_bf16 v[40:43], v[200:203], v[226:229], v[40:43]
	ds_read_b128 v[226:229], v195 offset:4096
	v_mfma_f32_16x16x32_bf16 v[44:47], v[200:203], v[230:233], v[44:47]
	ds_read_b128 v[230:233], v195 offset:6144
	v_mfma_f32_16x16x32_bf16 v[48:51], v[200:203], v[234:237], v[48:51]
	ds_read_b128 v[234:237], v195 offset:8192
	v_mfma_f32_16x16x32_bf16 v[52:55], v[200:203], v[238:241], v[52:55]
	ds_read_b128 v[238:241], v195 offset:10240
	v_mfma_f32_16x16x32_bf16 v[56:59], v[200:203], v[242:245], v[56:59]
	ds_read_b128 v[242:245], v195 offset:12288
	v_mfma_f32_16x16x32_bf16 v[60:63], v[200:203], v[246:249], v[60:63]
	ds_read_b128 v[246:249], v195 offset:14336
	ds_read_b128 v[200:203], v194 offset:6144
	s_add_i32 s1, s1, 2
	s_cmp_lt_i32 s1, s0
	s_cbranch_scc1 .Lgemm_kloop_rl
	s_waitcnt lgkmcnt(8)
	v_mfma_f32_16x16x32_bf16 v[64:67], v[160:163], v[204:207], v[64:67]
	s_waitcnt lgkmcnt(7)
	v_mfma_f32_16x16x32_bf16 v[68:71], v[160:163], v[222:225], v[68:71]
	s_waitcnt lgkmcnt(6)
	v_mfma_f32_16x16x32_bf16 v[72:75], v[160:163], v[226:229], v[72:75]
	v_mfma_f32_16x16x32_bf16 v[140:143], v[160:163], v[160:163], v[140:143]
	s_waitcnt lgkmcnt(5)
	v_mfma_f32_16x16x32_bf16 v[76:79], v[160:163], v[230:233], v[76:79]
	s_waitcnt lgkmcnt(4)
	v_mfma_f32_16x16x32_bf16 v[80:83], v[160:163], v[234:237], v[80:83]
	s_waitcnt lgkmcnt(3)
	v_mfma_f32_16x16x32_bf16 v[84:87], v[160:163], v[238:241], v[84:87]
	s_waitcnt lgkmcnt(2)
	v_mfma_f32_16x16x32_bf16 v[88:91], v[160:163], v[242:245], v[88:91]
	s_waitcnt lgkmcnt(1)
	v_mfma_f32_16x16x32_bf16 v[92:95], v[160:163], v[246:249], v[92:95]
	ds_read_b128 v[160:163], v215
	v_mfma_f32_16x16x32_bf16 v[96:99], v[176:179], v[204:207], v[96:99]
	v_mfma_f32_16x16x32_bf16 v[100:103], v[176:179], v[222:225], v[100:103]
	v_mfma_f32_16x16x32_bf16 v[104:107], v[176:179], v[226:229], v[104:107]
	v_mfma_f32_16x16x32_bf16 v[144:147], v[176:179], v[176:179], v[144:147]
	v_mfma_f32_16x16x32_bf16 v[108:111], v[176:179], v[230:233], v[108:111]
	v_mfma_f32_16x16x32_bf16 v[112:115], v[176:179], v[234:237], v[112:115]
	v_mfma_f32_16x16x32_bf16 v[116:119], v[176:179], v[238:241], v[116:119]
	v_mfma_f32_16x16x32_bf16 v[120:123], v[176:179], v[242:245], v[120:123]
	v_mfma_f32_16x16x32_bf16 v[124:127], v[176:179], v[246:249], v[124:127]
	ds_read_b128 v[176:179], v215 offset:2048
	v_mfma_f32_16x16x32_bf16 v[0:3], v[180:183], v[204:207], v[0:3]
	v_mfma_f32_16x16x32_bf16 v[4:7], v[180:183], v[222:225], v[4:7]
	v_mfma_f32_16x16x32_bf16 v[8:11], v[180:183], v[226:229], v[8:11]
	v_mfma_f32_16x16x32_bf16 v[148:151], v[180:183], v[180:183], v[148:151]
	v_mfma_f32_16x16x32_bf16 v[12:15], v[180:183], v[230:233], v[12:15]
	v_mfma_f32_16x16x32_bf16 v[16:19], v[180:183], v[234:237], v[16:19]
	v_mfma_f32_16x16x32_bf16 v[20:23], v[180:183], v[238:241], v[20:23]
	v_mfma_f32_16x16x32_bf16 v[24:27], v[180:183], v[242:245], v[24:27]
	v_mfma_f32_16x16x32_bf16 v[28:31], v[180:183], v[246:249], v[28:31]
	ds_read_b128 v[180:183], v215 offset:4096
	s_waitcnt lgkmcnt(3)
	v_mfma_f32_16x16x32_bf16 v[32:35], v[200:203], v[204:207], v[32:35]
	ds_read_b128 v[204:207], v197
	v_mfma_f32_16x16x32_bf16 v[36:39], v[200:203], v[222:225], v[36:39]
	ds_read_b128 v[222:225], v197 offset:2048
	v_mfma_f32_16x16x32_bf16 v[40:43], v[200:203], v[226:229], v[40:43]
	v_mfma_f32_16x16x32_bf16 v[152:155], v[200:203], v[200:203], v[152:155]
	ds_read_b128 v[226:229], v197 offset:4096
	v_mfma_f32_16x16x32_bf16 v[44:47], v[200:203], v[230:233], v[44:47]
	ds_read_b128 v[230:233], v197 offset:6144
	v_mfma_f32_16x16x32_bf16 v[48:51], v[200:203], v[234:237], v[48:51]
	ds_read_b128 v[234:237], v197 offset:8192
	v_mfma_f32_16x16x32_bf16 v[52:55], v[200:203], v[238:241], v[52:55]
	ds_read_b128 v[238:241], v197 offset:10240
	v_mfma_f32_16x16x32_bf16 v[56:59], v[200:203], v[242:245], v[56:59]
	ds_read_b128 v[242:245], v197 offset:12288
	v_mfma_f32_16x16x32_bf16 v[60:63], v[200:203], v[246:249], v[60:63]
	ds_read_b128 v[246:249], v197 offset:14336
	ds_read_b128 v[200:203], v215 offset:6144
	s_waitcnt lgkmcnt(8)
	v_mfma_f32_16x16x32_bf16 v[64:67], v[160:163], v[204:207], v[64:67]
	s_waitcnt lgkmcnt(7)
	v_mfma_f32_16x16x32_bf16 v[68:71], v[160:163], v[222:225], v[68:71]
	s_waitcnt lgkmcnt(6)
	v_mfma_f32_16x16x32_bf16 v[72:75], v[160:163], v[226:229], v[72:75]
	s_waitcnt lgkmcnt(5)
	v_mfma_f32_16x16x32_bf16 v[76:79], v[160:163], v[230:233], v[76:79]
	s_waitcnt lgkmcnt(4)
	v_mfma_f32_16x16x32_bf16 v[80:83], v[160:163], v[234:237], v[80:83]
	s_waitcnt lgkmcnt(3)
	v_mfma_f32_16x16x32_bf16 v[84:87], v[160:163], v[238:241], v[84:87]
	s_waitcnt lgkmcnt(2)
	v_mfma_f32_16x16x32_bf16 v[88:91], v[160:163], v[242:245], v[88:91]
	s_waitcnt lgkmcnt(1)
	v_mfma_f32_16x16x32_bf16 v[92:95], v[160:163], v[246:249], v[92:95]
	s_waitcnt vmcnt(0) lgkmcnt(0)
	s_barrier
; DI void lds_barrier() { asm volatile("s_waitcnt lgkmcnt(0)\n\ts_barrier" ::: "memory"); }
; DI void gemm_run(const GemmCfg c, char* smem, float* const g_h, u16* const g_hb, float* const g_out, const int final_out) {
;     ...
;     K_STEP(0, 1, 0, true, false);
;     lds_barrier();
;     K_STEP(1, 0, 0, false, false);
;     lds_barrier();
	ds_read_b128 v[160:163], v194 offset:36864
	v_mfma_f32_16x16x32_bf16 v[96:99], v[176:179], v[204:207], v[96:99]
	v_mfma_f32_16x16x32_bf16 v[100:103], v[176:179], v[222:225], v[100:103]
	v_mfma_f32_16x16x32_bf16 v[104:107], v[176:179], v[226:229], v[104:107]
	v_mfma_f32_16x16x32_bf16 v[108:111], v[176:179], v[230:233], v[108:111]
	v_mfma_f32_16x16x32_bf16 v[112:115], v[176:179], v[234:237], v[112:115]
	v_mfma_f32_16x16x32_bf16 v[116:119], v[176:179], v[238:241], v[116:119]
	v_mfma_f32_16x16x32_bf16 v[120:123], v[176:179], v[242:245], v[120:123]
	v_mfma_f32_16x16x32_bf16 v[124:127], v[176:179], v[246:249], v[124:127]
	ds_read_b128 v[176:179], v194 offset:38912
	v_mfma_f32_16x16x32_bf16 v[0:3], v[180:183], v[204:207], v[0:3]
	v_mfma_f32_16x16x32_bf16 v[4:7], v[180:183], v[222:225], v[4:7]
	v_mfma_f32_16x16x32_bf16 v[8:11], v[180:183], v[226:229], v[8:11]
	v_mfma_f32_16x16x32_bf16 v[12:15], v[180:183], v[230:233], v[12:15]
	v_mfma_f32_16x16x32_bf16 v[16:19], v[180:183], v[234:237], v[16:19]
	v_mfma_f32_16x16x32_bf16 v[20:23], v[180:183], v[238:241], v[20:23]
	v_mfma_f32_16x16x32_bf16 v[24:27], v[180:183], v[242:245], v[24:27]
	v_mfma_f32_16x16x32_bf16 v[28:31], v[180:183], v[246:249], v[28:31]
	ds_read_b128 v[180:183], v194 offset:40960
	v_mfma_f32_16x16x32_bf16 v[32:35], v[200:203], v[204:207], v[32:35]
	ds_read_b128 v[204:207], v195 offset:36864
	v_mfma_f32_16x16x32_bf16 v[36:39], v[200:203], v[222:225], v[36:39]
	ds_read_b128 v[222:225], v195 offset:38912
	v_mfma_f32_16x16x32_bf16 v[40:43], v[200:203], v[226:229], v[40:43]
	ds_read_b128 v[226:229], v195 offset:40960
	v_mfma_f32_16x16x32_bf16 v[44:47], v[200:203], v[230:233], v[44:47]
	ds_read_b128 v[230:233], v195 offset:43008
	v_mfma_f32_16x16x32_bf16 v[48:51], v[200:203], v[234:237], v[48:51]
	ds_read_b128 v[234:237], v195 offset:45056
	v_mfma_f32_16x16x32_bf16 v[52:55], v[200:203], v[238:241], v[52:55]
	ds_read_b128 v[238:241], v195 offset:47104
	v_mfma_f32_16x16x32_bf16 v[56:59], v[200:203], v[242:245], v[56:59]
	ds_read_b128 v[242:245], v195 offset:49152
	v_mfma_f32_16x16x32_bf16 v[60:63], v[200:203], v[246:249], v[60:63]
	ds_read_b128 v[246:249], v195 offset:51200
	ds_read_b128 v[200:203], v194 offset:43008
	s_waitcnt lgkmcnt(8)
	v_mfma_f32_16x16x32_bf16 v[64:67], v[160:163], v[204:207], v[64:67]
	s_waitcnt lgkmcnt(7)
	v_mfma_f32_16x16x32_bf16 v[68:71], v[160:163], v[222:225], v[68:71]
	s_waitcnt lgkmcnt(6)
	v_mfma_f32_16x16x32_bf16 v[72:75], v[160:163], v[226:229], v[72:75]
	v_mfma_f32_16x16x32_bf16 v[140:143], v[160:163], v[160:163], v[140:143]
	s_waitcnt lgkmcnt(5)
	v_mfma_f32_16x16x32_bf16 v[76:79], v[160:163], v[230:233], v[76:79]
	s_waitcnt lgkmcnt(4)
	v_mfma_f32_16x16x32_bf16 v[80:83], v[160:163], v[234:237], v[80:83]
	s_waitcnt lgkmcnt(3)
	v_mfma_f32_16x16x32_bf16 v[84:87], v[160:163], v[238:241], v[84:87]
	s_waitcnt lgkmcnt(2)
	v_mfma_f32_16x16x32_bf16 v[88:91], v[160:163], v[242:245], v[88:91]
	s_waitcnt lgkmcnt(1)
	v_mfma_f32_16x16x32_bf16 v[92:95], v[160:163], v[246:249], v[92:95]
	ds_read_b128 v[160:163], v215 offset:36864
	v_mfma_f32_16x16x32_bf16 v[96:99], v[176:179], v[204:207], v[96:99]
	v_mfma_f32_16x16x32_bf16 v[100:103], v[176:179], v[222:225], v[100:103]
	v_mfma_f32_16x16x32_bf16 v[104:107], v[176:179], v[226:229], v[104:107]
	v_mfma_f32_16x16x32_bf16 v[144:147], v[176:179], v[176:179], v[144:147]
	v_mfma_f32_16x16x32_bf16 v[108:111], v[176:179], v[230:233], v[108:111]
	v_mfma_f32_16x16x32_bf16 v[112:115], v[176:179], v[234:237], v[112:115]
	v_mfma_f32_16x16x32_bf16 v[116:119], v[176:179], v[238:241], v[116:119]
	v_mfma_f32_16x16x32_bf16 v[120:123], v[176:179], v[242:245], v[120:123]
	v_mfma_f32_16x16x32_bf16 v[124:127], v[176:179], v[246:249], v[124:127]
	ds_read_b128 v[176:179], v215 offset:38912
	v_mfma_f32_16x16x32_bf16 v[0:3], v[180:183], v[204:207], v[0:3]
	v_mfma_f32_16x16x32_bf16 v[4:7], v[180:183], v[222:225], v[4:7]
	v_mfma_f32_16x16x32_bf16 v[8:11], v[180:183], v[226:229], v[8:11]
	v_mfma_f32_16x16x32_bf16 v[148:151], v[180:183], v[180:183], v[148:151]
	v_mfma_f32_16x16x32_bf16 v[12:15], v[180:183], v[230:233], v[12:15]
	v_mfma_f32_16x16x32_bf16 v[16:19], v[180:183], v[234:237], v[16:19]
	v_mfma_f32_16x16x32_bf16 v[20:23], v[180:183], v[238:241], v[20:23]
	v_mfma_f32_16x16x32_bf16 v[24:27], v[180:183], v[242:245], v[24:27]
	v_mfma_f32_16x16x32_bf16 v[28:31], v[180:183], v[246:249], v[28:31]
	ds_read_b128 v[180:183], v215 offset:40960
	s_waitcnt lgkmcnt(3)
	v_mfma_f32_16x16x32_bf16 v[32:35], v[200:203], v[204:207], v[32:35]
	ds_read_b128 v[204:207], v197 offset:36864
	v_mfma_f32_16x16x32_bf16 v[36:39], v[200:203], v[222:225], v[36:39]
	ds_read_b128 v[222:225], v197 offset:38912
	v_mfma_f32_16x16x32_bf16 v[40:43], v[200:203], v[226:229], v[40:43]
	v_mfma_f32_16x16x32_bf16 v[152:155], v[200:203], v[200:203], v[152:155]
	ds_read_b128 v[226:229], v197 offset:40960
	v_mfma_f32_16x16x32_bf16 v[44:47], v[200:203], v[230:233], v[44:47]
	ds_read_b128 v[230:233], v197 offset:43008
	v_mfma_f32_16x16x32_bf16 v[48:51], v[200:203], v[234:237], v[48:51]
	ds_read_b128 v[234:237], v197 offset:45056
	v_mfma_f32_16x16x32_bf16 v[52:55], v[200:203], v[238:241], v[52:55]
	ds_read_b128 v[238:241], v197 offset:47104
	v_mfma_f32_16x16x32_bf16 v[56:59], v[200:203], v[242:245], v[56:59]
	ds_read_b128 v[242:245], v197 offset:49152
	v_mfma_f32_16x16x32_bf16 v[60:63], v[200:203], v[246:249], v[60:63]
	ds_read_b128 v[246:249], v197 offset:51200
	ds_read_b128 v[200:203], v215 offset:43008
	s_waitcnt lgkmcnt(8)
	v_mfma_f32_16x16x32_bf16 v[64:67], v[160:163], v[204:207], v[64:67]
	s_waitcnt lgkmcnt(7)
	v_mfma_f32_16x16x32_bf16 v[68:71], v[160:163], v[222:225], v[68:71]
	s_waitcnt lgkmcnt(6)
; DI void lds_barrier() { asm volatile("s_waitcnt lgkmcnt(0)\n\ts_barrier" ::: "memory"); }
; #define G_LOAD(RA, RB, KT) { size_t as_ = astep, bs_ = bstep; asm volatile("" : "+s"(as_), "+s"(bs_)); \
;       _Pragma("unroll") for (int i = 0; i < 4; ++i) { RA[i] = *(const u32x4*)(Ag + i * as_ + (KT) * 64); RB[i] = *(const u32x4*)(Bg + i * bs_ + (KT) * 64); } }
; DI void gemm_run(const GemmCfg c, char* smem, float* const g_h, u16* const g_hb, float* const g_out, const int final_out) {
;     ...
;     G_LOAD(ra0, rb0, 0);
;     __syncthreads();
;     G_STORE(ra0, rb0, 0);
;     G_LOAD(ra0, rb0, 1);
;     lds_barrier();
;     int kt = 0;
;     for (; kt + 3 < nk; kt += 2) {
;       K_STEP(0, 1, kt + 2, true, true);
;       lds_barrier();
;       K_STEP(1, 0, kt + 3, true, true);
;       lds_barrier();
;     }
	v_mfma_f32_16x16x32_bf16 v[72:75], v[160:163], v[226:229], v[72:75]
	s_waitcnt lgkmcnt(5)
	v_mfma_f32_16x16x32_bf16 v[76:79], v[160:163], v[230:233], v[76:79]
	s_waitcnt lgkmcnt(4)
	v_mfma_f32_16x16x32_bf16 v[80:83], v[160:163], v[234:237], v[80:83]
	s_waitcnt lgkmcnt(3)
	v_mfma_f32_16x16x32_bf16 v[84:87], v[160:163], v[238:241], v[84:87]
	s_waitcnt lgkmcnt(2)
	v_mfma_f32_16x16x32_bf16 v[88:91], v[160:163], v[242:245], v[88:91]
	s_waitcnt lgkmcnt(1)
	v_mfma_f32_16x16x32_bf16 v[92:95], v[160:163], v[246:249], v[92:95]
	v_mfma_f32_16x16x32_bf16 v[96:99], v[176:179], v[204:207], v[96:99]
	v_mfma_f32_16x16x32_bf16 v[100:103], v[176:179], v[222:225], v[100:103]
	v_mfma_f32_16x16x32_bf16 v[104:107], v[176:179], v[226:229], v[104:107]
	v_mfma_f32_16x16x32_bf16 v[108:111], v[176:179], v[230:233], v[108:111]
	v_mfma_f32_16x16x32_bf16 v[112:115], v[176:179], v[234:237], v[112:115]
	v_mfma_f32_16x16x32_bf16 v[116:119], v[176:179], v[238:241], v[116:119]
	v_mfma_f32_16x16x32_bf16 v[120:123], v[176:179], v[242:245], v[120:123]
	v_mfma_f32_16x16x32_bf16 v[124:127], v[176:179], v[246:249], v[124:127]
	v_mfma_f32_16x16x32_bf16 v[0:3], v[180:183], v[204:207], v[0:3]
	v_mfma_f32_16x16x32_bf16 v[4:7], v[180:183], v[222:225], v[4:7]
	v_mfma_f32_16x16x32_bf16 v[8:11], v[180:183], v[226:229], v[8:11]
	v_mfma_f32_16x16x32_bf16 v[12:15], v[180:183], v[230:233], v[12:15]
	v_mfma_f32_16x16x32_bf16 v[16:19], v[180:183], v[234:237], v[16:19]
	v_mfma_f32_16x16x32_bf16 v[20:23], v[180:183], v[238:241], v[20:23]
	v_mfma_f32_16x16x32_bf16 v[24:27], v[180:183], v[242:245], v[24:27]
	v_mfma_f32_16x16x32_bf16 v[28:31], v[180:183], v[246:249], v[28:31]
	s_waitcnt lgkmcnt(0)
	v_mfma_f32_16x16x32_bf16 v[32:35], v[200:203], v[204:207], v[32:35]
	v_mfma_f32_16x16x32_bf16 v[36:39], v[200:203], v[222:225], v[36:39]
	v_mfma_f32_16x16x32_bf16 v[40:43], v[200:203], v[226:229], v[40:43]
	v_mfma_f32_16x16x32_bf16 v[44:47], v[200:203], v[230:233], v[44:47]
	v_mfma_f32_16x16x32_bf16 v[48:51], v[200:203], v[234:237], v[48:51]
	v_mfma_f32_16x16x32_bf16 v[52:55], v[200:203], v[238:241], v[52:55]
	v_mfma_f32_16x16x32_bf16 v[56:59], v[200:203], v[242:245], v[56:59]
	v_mfma_f32_16x16x32_bf16 v[60:63], v[200:203], v[246:249], v[60:63]
	s_branch .Lgemm_kdone
.Lgemm_kloop_r1l:
	s_waitcnt lgkmcnt(8)
	v_mfma_f32_16x16x32_bf16 v[64:67], v[160:163], v[204:207], v[64:67]
	s_waitcnt lgkmcnt(7)
	v_mfma_f32_16x16x32_bf16 v[68:71], v[160:163], v[222:225], v[68:71]
	s_waitcnt lgkmcnt(6)
	v_mfma_f32_16x16x32_bf16 v[72:75], v[160:163], v[226:229], v[72:75]
	s_waitcnt lgkmcnt(5)
	v_mfma_f32_16x16x32_bf16 v[76:79], v[160:163], v[230:233], v[76:79]
	s_waitcnt lgkmcnt(4)
	v_mfma_f32_16x16x32_bf16 v[80:83], v[160:163], v[234:237], v[80:83]
	s_waitcnt lgkmcnt(3)
	v_mfma_f32_16x16x32_bf16 v[84:87], v[160:163], v[238:241], v[84:87]
	s_waitcnt lgkmcnt(2)
	v_mfma_f32_16x16x32_bf16 v[88:91], v[160:163], v[242:245], v[88:91]
	s_waitcnt lgkmcnt(1)
	v_mfma_f32_16x16x32_bf16 v[92:95], v[160:163], v[246:249], v[92:95]
	ds_read_b128 v[160:163], v215
	v_mfma_f32_16x16x32_bf16 v[96:99], v[176:179], v[204:207], v[96:99]
	v_mfma_f32_16x16x32_bf16 v[100:103], v[176:179], v[222:225], v[100:103]
	v_mfma_f32_16x16x32_bf16 v[104:107], v[176:179], v[226:229], v[104:107]
	v_mfma_f32_16x16x32_bf16 v[108:111], v[176:179], v[230:233], v[108:111]
	v_mfma_f32_16x16x32_bf16 v[112:115], v[176:179], v[234:237], v[112:115]
	v_mfma_f32_16x16x32_bf16 v[116:119], v[176:179], v[238:241], v[116:119]
	v_mfma_f32_16x16x32_bf16 v[120:123], v[176:179], v[242:245], v[120:123]
	v_mfma_f32_16x16x32_bf16 v[124:127], v[176:179], v[246:249], v[124:127]
	ds_read_b128 v[176:179], v215 offset:2048
	v_mfma_f32_16x16x32_bf16 v[0:3], v[180:183], v[204:207], v[0:3]
	v_mfma_f32_16x16x32_bf16 v[4:7], v[180:183], v[222:225], v[4:7]
	v_mfma_f32_16x16x32_bf16 v[8:11], v[180:183], v[226:229], v[8:11]
	v_mfma_f32_16x16x32_bf16 v[12:15], v[180:183], v[230:233], v[12:15]
	v_mfma_f32_16x16x32_bf16 v[16:19], v[180:183], v[234:237], v[16:19]
	v_mfma_f32_16x16x32_bf16 v[20:23], v[180:183], v[238:241], v[20:23]
	v_mfma_f32_16x16x32_bf16 v[24:27], v[180:183], v[242:245], v[24:27]
	v_mfma_f32_16x16x32_bf16 v[28:31], v[180:183], v[246:249], v[28:31]
	ds_read_b128 v[180:183], v215 offset:4096
	s_waitcnt lgkmcnt(3)
	v_mfma_f32_16x16x32_bf16 v[32:35], v[200:203], v[204:207], v[32:35]
	ds_read_b128 v[204:207], v197
	v_mfma_f32_16x16x32_bf16 v[36:39], v[200:203], v[222:225], v[36:39]
	ds_read_b128 v[222:225], v197 offset:2048
	v_mfma_f32_16x16x32_bf16 v[40:43], v[200:203], v[226:229], v[40:43]
	ds_read_b128 v[226:229], v197 offset:4096
	v_mfma_f32_16x16x32_bf16 v[44:47], v[200:203], v[230:233], v[44:47]
	ds_read_b128 v[230:233], v197 offset:6144
	v_mfma_f32_16x16x32_bf16 v[48:51], v[200:203], v[234:237], v[48:51]
	ds_read_b128 v[234:237], v197 offset:8192
	v_mfma_f32_16x16x32_bf16 v[52:55], v[200:203], v[238:241], v[52:55]
	ds_read_b128 v[238:241], v197 offset:10240
	v_mfma_f32_16x16x32_bf16 v[56:59], v[200:203], v[242:245], v[56:59]
	ds_read_b128 v[242:245], v197 offset:12288
	v_mfma_f32_16x16x32_bf16 v[60:63], v[200:203], v[246:249], v[60:63]
	ds_read_b128 v[246:249], v197 offset:14336
	ds_read_b128 v[200:203], v215 offset:6144
	s_waitcnt lgkmcnt(8)
	v_mfma_f32_16x16x32_bf16 v[64:67], v[160:163], v[204:207], v[64:67]
	s_waitcnt lgkmcnt(7)
	v_mfma_f32_16x16x32_bf16 v[68:71], v[160:163], v[222:225], v[68:71]
	s_waitcnt lgkmcnt(6)
	v_mfma_f32_16x16x32_bf16 v[72:75], v[160:163], v[226:229], v[72:75]
	v_mfma_f32_16x16x32_bf16 v[140:143], v[160:163], v[160:163], v[140:143]
	s_waitcnt lgkmcnt(5)
	v_mfma_f32_16x16x32_bf16 v[76:79], v[160:163], v[230:233], v[76:79]
	s_waitcnt lgkmcnt(4)
	v_mfma_f32_16x16x32_bf16 v[80:83], v[160:163], v[234:237], v[80:83]
	s_waitcnt lgkmcnt(3)
	v_mfma_f32_16x16x32_bf16 v[84:87], v[160:163], v[238:241], v[84:87]
	s_waitcnt lgkmcnt(2)
	v_mfma_f32_16x16x32_bf16 v[88:91], v[160:163], v[242:245], v[88:91]
	s_waitcnt lgkmcnt(1)
	v_mfma_f32_16x16x32_bf16 v[92:95], v[160:163], v[246:249], v[92:95]
	s_waitcnt vmcnt(0) lgkmcnt(0)
	s_barrier
; DI void lds_barrier() { asm volatile("s_waitcnt lgkmcnt(0)\n\ts_barrier" ::: "memory"); }
; #define G_LOAD(RA, RB, KT) { size_t as_ = astep, bs_ = bstep; asm volatile("" : "+s"(as_), "+s"(bs_)); \
;       _Pragma("unroll") for (int i = 0; i < 4; ++i) { RA[i] = *(const u32x4*)(Ag + i * as_ + (KT) * 64); RB[i] = *(const u32x4*)(Bg + i * bs_ + (KT) * 64); } }
; DI void gemm_run(const GemmCfg c, char* smem, float* const g_h, u16* const g_hb, float* const g_out, const int final_out) {
;     ...
;     G_LOAD(ra0, rb0, 0);
;     __syncthreads();
;     G_STORE(ra0, rb0, 0);
;     G_LOAD(ra0, rb0, 1);
;     lds_barrier();
;     int kt = 0;
;     for (; kt + 3 < nk; kt += 2) {
;       K_STEP(0, 1, kt + 2, true, true);
;       lds_barrier();
;       K_STEP(1, 0, kt + 3, true, true);
;       lds_barrier();
;     }
	ds_read_b128 v[160:163], v194 offset:36864
	v_mfma_f32_16x16x32_bf16 v[96:99], v[176:179], v[204:207], v[96:99]
	v_mfma_f32_16x16x32_bf16 v[100:103], v[176:179], v[222:225], v[100:103]
	v_mfma_f32_16x16x32_bf16 v[104:107], v[176:179], v[226:229], v[104:107]
	v_mfma_f32_16x16x32_bf16 v[144:147], v[176:179], v[176:179], v[144:147]
	v_mfma_f32_16x16x32_bf16 v[108:111], v[176:179], v[230:233], v[108:111]
	v_mfma_f32_16x16x32_bf16 v[112:115], v[176:179], v[234:237], v[112:115]
	v_mfma_f32_16x16x32_bf16 v[116:119], v[176:179], v[238:241], v[116:119]
	v_mfma_f32_16x16x32_bf16 v[120:123], v[176:179], v[242:245], v[120:123]
	v_mfma_f32_16x16x32_bf16 v[124:127], v[176:179], v[246:249], v[124:127]
	s_add_u32 m0, s8, 0x0
	ds_read_b128 v[176:179], v194 offset:38912
	v_mfma_f32_16x16x32_bf16 v[0:3], v[180:183], v[204:207], v[0:3]
	global_load_lds_dwordx4 v130, s[4:5]
	s_add_u32 m0, s8, 0x12000
	v_mfma_f32_16x16x32_bf16 v[4:7], v[180:183], v[222:225], v[4:7]
	global_load_lds_dwordx4 v134, s[6:7]
	s_add_u32 m0, s8, 0x400
	v_mfma_f32_16x16x32_bf16 v[8:11], v[180:183], v[226:229], v[8:11]
	v_mfma_f32_16x16x32_bf16 v[148:151], v[180:183], v[180:183], v[148:151]
	global_load_lds_dwordx4 v131, s[4:5]
	s_add_u32 m0, s8, 0x12400
	v_mfma_f32_16x16x32_bf16 v[12:15], v[180:183], v[230:233], v[12:15]
	global_load_lds_dwordx4 v135, s[6:7]
	s_add_u32 m0, s8, 0x800
	v_mfma_f32_16x16x32_bf16 v[16:19], v[180:183], v[234:237], v[16:19]
	global_load_lds_dwordx4 v132, s[4:5]
	s_add_u32 m0, s8, 0x12800
	v_mfma_f32_16x16x32_bf16 v[20:23], v[180:183], v[238:241], v[20:23]
	global_load_lds_dwordx4 v136, s[6:7]
	s_add_u32 m0, s8, 0xc00
	v_mfma_f32_16x16x32_bf16 v[24:27], v[180:183], v[242:245], v[24:27]
	global_load_lds_dwordx4 v133, s[4:5]
	s_add_u32 m0, s8, 0x12c00
	v_mfma_f32_16x16x32_bf16 v[28:31], v[180:183], v[246:249], v[28:31]
	global_load_lds_dwordx4 v137, s[6:7]
	ds_read_b128 v[180:183], v194 offset:40960
	v_mfma_f32_16x16x32_bf16 v[32:35], v[200:203], v[204:207], v[32:35]
	s_add_u32 s4, s4, 0x80
	s_addc_u32 s5, s5, 0
	s_add_u32 s6, s6, 0x80
	s_addc_u32 s7, s7, 0
	ds_read_b128 v[204:207], v195 offset:36864
	v_mfma_f32_16x16x32_bf16 v[36:39], v[200:203], v[222:225], v[36:39]
	ds_read_b128 v[222:225], v195 offset:38912
	v_mfma_f32_16x16x32_bf16 v[40:43], v[200:203], v[226:229], v[40:43]
	v_mfma_f32_16x16x32_bf16 v[152:155], v[200:203], v[200:203], v[152:155]
	ds_read_b128 v[226:229], v195 offset:40960
	v_mfma_f32_16x16x32_bf16 v[44:47], v[200:203], v[230:233], v[44:47]
	ds_read_b128 v[230:233], v195 offset:43008
	v_mfma_f32_16x16x32_bf16 v[48:51], v[200:203], v[234:237], v[48:51]
	ds_read_b128 v[234:237], v195 offset:45056
	v_mfma_f32_16x16x32_bf16 v[52:55], v[200:203], v[238:241], v[52:55]
	ds_read_b128 v[238:241], v195 offset:47104
	v_mfma_f32_16x16x32_bf16 v[56:59], v[200:203], v[242:245], v[56:59]
	ds_read_b128 v[242:245], v195 offset:49152
	v_mfma_f32_16x16x32_bf16 v[60:63], v[200:203], v[246:249], v[60:63]
	ds_read_b128 v[246:249], v195 offset:51200
	ds_read_b128 v[200:203], v194 offset:43008
	s_waitcnt lgkmcnt(8)
	v_mfma_f32_16x16x32_bf16 v[64:67], v[160:163], v[204:207], v[64:67]
	s_waitcnt lgkmcnt(7)
	v_mfma_f32_16x16x32_bf16 v[68:71], v[160:163], v[222:225], v[68:71]
	s_waitcnt lgkmcnt(6)
	v_mfma_f32_16x16x32_bf16 v[72:75], v[160:163], v[226:229], v[72:75]
	s_waitcnt lgkmcnt(5)
	v_mfma_f32_16x16x32_bf16 v[76:79], v[160:163], v[230:233], v[76:79]
	s_waitcnt lgkmcnt(4)
	v_mfma_f32_16x16x32_bf16 v[80:83], v[160:163], v[234:237], v[80:83]
	s_waitcnt lgkmcnt(3)
	v_mfma_f32_16x16x32_bf16 v[84:87], v[160:163], v[238:241], v[84:87]
	s_waitcnt lgkmcnt(2)
	v_mfma_f32_16x16x32_bf16 v[88:91], v[160:163], v[242:245], v[88:91]
	s_waitcnt lgkmcnt(1)
	v_mfma_f32_16x16x32_bf16 v[92:95], v[160:163], v[246:249], v[92:95]
	ds_read_b128 v[160:163], v215 offset:36864
	v_mfma_f32_16x16x32_bf16 v[96:99], v[176:179], v[204:207], v[96:99]
	v_mfma_f32_16x16x32_bf16 v[100:103], v[176:179], v[222:225], v[100:103]
	v_mfma_f32_16x16x32_bf16 v[104:107], v[176:179], v[226:229], v[104:107]
	v_mfma_f32_16x16x32_bf16 v[108:111], v[176:179], v[230:233], v[108:111]
	v_mfma_f32_16x16x32_bf16 v[112:115], v[176:179], v[234:237], v[112:115]
	v_mfma_f32_16x16x32_bf16 v[116:119], v[176:179], v[238:241], v[116:119]
	v_mfma_f32_16x16x32_bf16 v[120:123], v[176:179], v[242:245], v[120:123]
	v_mfma_f32_16x16x32_bf16 v[124:127], v[176:179], v[246:249], v[124:127]
	ds_read_b128 v[176:179], v215 offset:38912
	v_mfma_f32_16x16x32_bf16 v[0:3], v[180:183], v[204:207], v[0:3]
	v_mfma_f32_16x16x32_bf16 v[4:7], v[180:183], v[222:225], v[4:7]
	v_mfma_f32_16x16x32_bf16 v[8:11], v[180:183], v[226:229], v[8:11]
	v_mfma_f32_16x16x32_bf16 v[12:15], v[180:183], v[230:233], v[12:15]
	v_mfma_f32_16x16x32_bf16 v[16:19], v[180:183], v[234:237], v[16:19]
	v_mfma_f32_16x16x32_bf16 v[20:23], v[180:183], v[238:241], v[20:23]
	v_mfma_f32_16x16x32_bf16 v[24:27], v[180:183], v[242:245], v[24:27]
	v_mfma_f32_16x16x32_bf16 v[28:31], v[180:183], v[246:249], v[28:31]
	ds_read_b128 v[180:183], v215 offset:40960
	s_waitcnt lgkmcnt(3)
	v_mfma_f32_16x16x32_bf16 v[32:35], v[200:203], v[204:207], v[32:35]
	ds_read_b128 v[204:207], v197 offset:36864
	v_mfma_f32_16x16x32_bf16 v[36:39], v[200:203], v[222:225], v[36:39]
	ds_read_b128 v[222:225], v197 offset:38912
	v_mfma_f32_16x16x32_bf16 v[40:43], v[200:203], v[226:229], v[40:43]
	ds_read_b128 v[226:229], v197 offset:40960
	v_mfma_f32_16x16x32_bf16 v[44:47], v[200:203], v[230:233], v[44:47]
	ds_read_b128 v[230:233], v197 offset:43008
	v_mfma_f32_16x16x32_bf16 v[48:51], v[200:203], v[234:237], v[48:51]
	ds_read_b128 v[234:237], v197 offset:45056
	v_mfma_f32_16x16x32_bf16 v[52:55], v[200:203], v[238:241], v[52:55]
	ds_read_b128 v[238:241], v197 offset:47104
	v_mfma_f32_16x16x32_bf16 v[56:59], v[200:203], v[242:245], v[56:59]
	ds_read_b128 v[242:245], v197 offset:49152
	v_mfma_f32_16x16x32_bf16 v[60:63], v[200:203], v[246:249], v[60:63]
	ds_read_b128 v[246:249], v197 offset:51200
	ds_read_b128 v[200:203], v215 offset:43008
	s_waitcnt lgkmcnt(8)
	v_mfma_f32_16x16x32_bf16 v[64:67], v[160:163], v[204:207], v[64:67]
	s_waitcnt lgkmcnt(7)
	v_mfma_f32_16x16x32_bf16 v[68:71], v[160:163], v[222:225], v[68:71]
	s_waitcnt lgkmcnt(6)
	v_mfma_f32_16x16x32_bf16 v[72:75], v[160:163], v[226:229], v[72:75]
	v_mfma_f32_16x16x32_bf16 v[140:143], v[160:163], v[160:163], v[140:143]
	s_waitcnt lgkmcnt(5)
	v_mfma_f32_16x16x32_bf16 v[76:79], v[160:163], v[230:233], v[76:79]
	s_waitcnt lgkmcnt(4)
	v_mfma_f32_16x16x32_bf16 v[80:83], v[160:163], v[234:237], v[80:83]
	s_waitcnt lgkmcnt(3)
	v_mfma_f32_16x16x32_bf16 v[84:87], v[160:163], v[238:241], v[84:87]
	s_waitcnt lgkmcnt(2)
	v_mfma_f32_16x16x32_bf16 v[88:91], v[160:163], v[242:245], v[88:91]
	s_waitcnt lgkmcnt(1)
	v_mfma_f32_16x16x32_bf16 v[92:95], v[160:163], v[246:249], v[92:95]
	s_waitcnt vmcnt(0) lgkmcnt(0)
	s_barrier
; DI void lds_barrier() { asm volatile("s_waitcnt lgkmcnt(0)\n\ts_barrier" ::: "memory"); }
; #define G_LOAD(RA, RB, KT) { size_t as_ = astep, bs_ = bstep; asm volatile("" : "+s"(as_), "+s"(bs_)); \
;       _Pragma("unroll") for (int i = 0; i < 4; ++i) { RA[i] = *(const u32x4*)(Ag + i * as_ + (KT) * 64); RB[i] = *(const u32x4*)(Bg + i * bs_ + (KT) * 64); } }
; DI void gemm_run(const GemmCfg c, char* smem, float* const g_h, u16* const g_hb, float* const g_out, const int final_out) {
;     ...
;     G_LOAD(ra0, rb0, 0);
;     __syncthreads();
;     G_STORE(ra0, rb0, 0);
;     G_LOAD(ra0, rb0, 1);
;     lds_barrier();
;     int kt = 0;
;     for (; kt + 3 < nk; kt += 2) {
;       K_STEP(0, 1, kt + 2, true, true);
;       lds_barrier();
;       K_STEP(1, 0, kt + 3, true, true);
;       lds_barrier();
;     }
;     K_STEP(0, 1, 0, true, false);
;     lds_barrier();
;     K_STEP(1, 0, 0, false, false);
;     lds_barrier();
	ds_read_b128 v[160:163], v194
	v_mfma_f32_16x16x32_bf16 v[96:99], v[176:179], v[204:207], v[96:99]
	v_mfma_f32_16x16x32_bf16 v[100:103], v[176:179], v[222:225], v[100:103]
	v_mfma_f32_16x16x32_bf16 v[104:107], v[176:179], v[226:229], v[104:107]
	v_mfma_f32_16x16x32_bf16 v[144:147], v[176:179], v[176:179], v[144:147]
	v_mfma_f32_16x16x32_bf16 v[108:111], v[176:179], v[230:233], v[108:111]
	v_mfma_f32_16x16x32_bf16 v[112:115], v[176:179], v[234:237], v[112:115]
	v_mfma_f32_16x16x32_bf16 v[116:119], v[176:179], v[238:241], v[116:119]
	v_mfma_f32_16x16x32_bf16 v[120:123], v[176:179], v[242:245], v[120:123]
	v_mfma_f32_16x16x32_bf16 v[124:127], v[176:179], v[246:249], v[124:127]
	s_add_u32 m0, s8, 0x9000
	ds_read_b128 v[176:179], v194 offset:2048
	v_mfma_f32_16x16x32_bf16 v[0:3], v[180:183], v[204:207], v[0:3]
	global_load_lds_dwordx4 v130, s[4:5]
	s_add_u32 m0, s8, 0x1b000
	v_mfma_f32_16x16x32_bf16 v[4:7], v[180:183], v[222:225], v[4:7]
	global_load_lds_dwordx4 v134, s[6:7]
	s_add_u32 m0, s8, 0x9400
	v_mfma_f32_16x16x32_bf16 v[8:11], v[180:183], v[226:229], v[8:11]
	v_mfma_f32_16x16x32_bf16 v[148:151], v[180:183], v[180:183], v[148:151]
	global_load_lds_dwordx4 v131, s[4:5]
	s_add_u32 m0, s8, 0x1b400
	v_mfma_f32_16x16x32_bf16 v[12:15], v[180:183], v[230:233], v[12:15]
	global_load_lds_dwordx4 v135, s[6:7]
	s_add_u32 m0, s8, 0x9800
	v_mfma_f32_16x16x32_bf16 v[16:19], v[180:183], v[234:237], v[16:19]
	global_load_lds_dwordx4 v132, s[4:5]
	s_add_u32 m0, s8, 0x1b800
	v_mfma_f32_16x16x32_bf16 v[20:23], v[180:183], v[238:241], v[20:23]
	global_load_lds_dwordx4 v136, s[6:7]
	s_add_u32 m0, s8, 0x9c00
	v_mfma_f32_16x16x32_bf16 v[24:27], v[180:183], v[242:245], v[24:27]
	global_load_lds_dwordx4 v133, s[4:5]
	s_add_u32 m0, s8, 0x1bc00
	v_mfma_f32_16x16x32_bf16 v[28:31], v[180:183], v[246:249], v[28:31]
	global_load_lds_dwordx4 v137, s[6:7]
	ds_read_b128 v[180:183], v194 offset:4096
	v_mfma_f32_16x16x32_bf16 v[32:35], v[200:203], v[204:207], v[32:35]
	s_add_u32 s4, s4, 0x80
	s_addc_u32 s5, s5, 0
	s_add_u32 s6, s6, 0x80
	s_addc_u32 s7, s7, 0
	ds_read_b128 v[204:207], v195
	v_mfma_f32_16x16x32_bf16 v[36:39], v[200:203], v[222:225], v[36:39]
	ds_read_b128 v[222:225], v195 offset:2048
	v_mfma_f32_16x16x32_bf16 v[40:43], v[200:203], v[226:229], v[40:43]
	v_mfma_f32_16x16x32_bf16 v[152:155], v[200:203], v[200:203], v[152:155]
	ds_read_b128 v[226:229], v195 offset:4096
	v_mfma_f32_16x16x32_bf16 v[44:47], v[200:203], v[230:233], v[44:47]
	ds_read_b128 v[230:233], v195 offset:6144
	v_mfma_f32_16x16x32_bf16 v[48:51], v[200:203], v[234:237], v[48:51]
	ds_read_b128 v[234:237], v195 offset:8192
	v_mfma_f32_16x16x32_bf16 v[52:55], v[200:203], v[238:241], v[52:55]
	ds_read_b128 v[238:241], v195 offset:10240
	v_mfma_f32_16x16x32_bf16 v[56:59], v[200:203], v[242:245], v[56:59]
	ds_read_b128 v[242:245], v195 offset:12288
	v_mfma_f32_16x16x32_bf16 v[60:63], v[200:203], v[246:249], v[60:63]
	ds_read_b128 v[246:249], v195 offset:14336
	ds_read_b128 v[200:203], v194 offset:6144
	s_add_i32 s1, s1, 2
	s_cmp_lt_i32 s1, s0
	s_cbranch_scc1 .Lgemm_kloop_r1l
	s_waitcnt lgkmcnt(8)
	v_mfma_f32_16x16x32_bf16 v[64:67], v[160:163], v[204:207], v[64:67]
	s_waitcnt lgkmcnt(7)
	v_mfma_f32_16x16x32_bf16 v[68:71], v[160:163], v[222:225], v[68:71]
	s_waitcnt lgkmcnt(6)
	v_mfma_f32_16x16x32_bf16 v[72:75], v[160:163], v[226:229], v[72:75]
	s_waitcnt lgkmcnt(5)
	v_mfma_f32_16x16x32_bf16 v[76:79], v[160:163], v[230:233], v[76:79]
	s_waitcnt lgkmcnt(4)
	v_mfma_f32_16x16x32_bf16 v[80:83], v[160:163], v[234:237], v[80:83]
	s_waitcnt lgkmcnt(3)
	v_mfma_f32_16x16x32_bf16 v[84:87], v[160:163], v[238:241], v[84:87]
	s_waitcnt lgkmcnt(2)
	v_mfma_f32_16x16x32_bf16 v[88:91], v[160:163], v[242:245], v[88:91]
	s_waitcnt lgkmcnt(1)
	v_mfma_f32_16x16x32_bf16 v[92:95], v[160:163], v[246:249], v[92:95]
	ds_read_b128 v[160:163], v215
	v_mfma_f32_16x16x32_bf16 v[96:99], v[176:179], v[204:207], v[96:99]
	v_mfma_f32_16x16x32_bf16 v[100:103], v[176:179], v[222:225], v[100:103]
	v_mfma_f32_16x16x32_bf16 v[104:107], v[176:179], v[226:229], v[104:107]
	v_mfma_f32_16x16x32_bf16 v[108:111], v[176:179], v[230:233], v[108:111]
	v_mfma_f32_16x16x32_bf16 v[112:115], v[176:179], v[234:237], v[112:115]
	v_mfma_f32_16x16x32_bf16 v[116:119], v[176:179], v[238:241], v[116:119]
	v_mfma_f32_16x16x32_bf16 v[120:123], v[176:179], v[242:245], v[120:123]
	v_mfma_f32_16x16x32_bf16 v[124:127], v[176:179], v[246:249], v[124:127]
	ds_read_b128 v[176:179], v215 offset:2048
	v_mfma_f32_16x16x32_bf16 v[0:3], v[180:183], v[204:207], v[0:3]
	v_mfma_f32_16x16x32_bf16 v[4:7], v[180:183], v[222:225], v[4:7]
	v_mfma_f32_16x16x32_bf16 v[8:11], v[180:183], v[226:229], v[8:11]
	v_mfma_f32_16x16x32_bf16 v[12:15], v[180:183], v[230:233], v[12:15]
	v_mfma_f32_16x16x32_bf16 v[16:19], v[180:183], v[234:237], v[16:19]
	v_mfma_f32_16x16x32_bf16 v[20:23], v[180:183], v[238:241], v[20:23]
	v_mfma_f32_16x16x32_bf16 v[24:27], v[180:183], v[242:245], v[24:27]
	v_mfma_f32_16x16x32_bf16 v[28:31], v[180:183], v[246:249], v[28:31]
	ds_read_b128 v[180:183], v215 offset:4096
	s_waitcnt lgkmcnt(3)
	v_mfma_f32_16x16x32_bf16 v[32:35], v[200:203], v[204:207], v[32:35]
	ds_read_b128 v[204:207], v197
	v_mfma_f32_16x16x32_bf16 v[36:39], v[200:203], v[222:225], v[36:39]
	ds_read_b128 v[222:225], v197 offset:2048
	v_mfma_f32_16x16x32_bf16 v[40:43], v[200:203], v[226:229], v[40:43]
	ds_read_b128 v[226:229], v197 offset:4096
	v_mfma_f32_16x16x32_bf16 v[44:47], v[200:203], v[230:233], v[44:47]
	ds_read_b128 v[230:233], v197 offset:6144
	v_mfma_f32_16x16x32_bf16 v[48:51], v[200:203], v[234:237], v[48:51]
	ds_read_b128 v[234:237], v197 offset:8192
	v_mfma_f32_16x16x32_bf16 v[52:55], v[200:203], v[238:241], v[52:55]
	ds_read_b128 v[238:241], v197 offset:10240
	v_mfma_f32_16x16x32_bf16 v[56:59], v[200:203], v[242:245], v[56:59]
	ds_read_b128 v[242:245], v197 offset:12288
	v_mfma_f32_16x16x32_bf16 v[60:63], v[200:203], v[246:249], v[60:63]
	ds_read_b128 v[246:249], v197 offset:14336
	ds_read_b128 v[200:203], v215 offset:6144
	s_waitcnt lgkmcnt(8)
	v_mfma_f32_16x16x32_bf16 v[64:67], v[160:163], v[204:207], v[64:67]
	s_waitcnt lgkmcnt(7)
	v_mfma_f32_16x16x32_bf16 v[68:71], v[160:163], v[222:225], v[68:71]
	s_waitcnt lgkmcnt(6)
	v_mfma_f32_16x16x32_bf16 v[72:75], v[160:163], v[226:229], v[72:75]
	v_mfma_f32_16x16x32_bf16 v[140:143], v[160:163], v[160:163], v[140:143]
	s_waitcnt lgkmcnt(5)
	v_mfma_f32_16x16x32_bf16 v[76:79], v[160:163], v[230:233], v[76:79]
	s_waitcnt lgkmcnt(4)
	v_mfma_f32_16x16x32_bf16 v[80:83], v[160:163], v[234:237], v[80:83]
	s_waitcnt lgkmcnt(3)
	v_mfma_f32_16x16x32_bf16 v[84:87], v[160:163], v[238:241], v[84:87]
	s_waitcnt lgkmcnt(2)
	v_mfma_f32_16x16x32_bf16 v[88:91], v[160:163], v[242:245], v[88:91]
	s_waitcnt lgkmcnt(1)
	v_mfma_f32_16x16x32_bf16 v[92:95], v[160:163], v[246:249], v[92:95]
	s_waitcnt vmcnt(0) lgkmcnt(0)
	s_barrier
; DI void lds_barrier() { asm volatile("s_waitcnt lgkmcnt(0)\n\ts_barrier" ::: "memory"); }
; DI void gemm_run(const GemmCfg c, char* smem, float* const g_h, u16* const g_hb, float* const g_out, const int final_out) {
;     ...
;     K_STEP(0, 1, 0, true, false);
;     lds_barrier();
;     K_STEP(1, 0, 0, false, false);
;     lds_barrier();
	ds_read_b128 v[160:163], v194 offset:36864
	v_mfma_f32_16x16x32_bf16 v[96:99], v[176:179], v[204:207], v[96:99]
	v_mfma_f32_16x16x32_bf16 v[100:103], v[176:179], v[222:225], v[100:103]
	v_mfma_f32_16x16x32_bf16 v[104:107], v[176:179], v[226:229], v[104:107]
	v_mfma_f32_16x16x32_bf16 v[144:147], v[176:179], v[176:179], v[144:147]
	v_mfma_f32_16x16x32_bf16 v[108:111], v[176:179], v[230:233], v[108:111]
	v_mfma_f32_16x16x32_bf16 v[112:115], v[176:179], v[234:237], v[112:115]
	v_mfma_f32_16x16x32_bf16 v[116:119], v[176:179], v[238:241], v[116:119]
	v_mfma_f32_16x16x32_bf16 v[120:123], v[176:179], v[242:245], v[120:123]
	v_mfma_f32_16x16x32_bf16 v[124:127], v[176:179], v[246:249], v[124:127]
	ds_read_b128 v[176:179], v194 offset:38912
	v_mfma_f32_16x16x32_bf16 v[0:3], v[180:183], v[204:207], v[0:3]
	v_mfma_f32_16x16x32_bf16 v[4:7], v[180:183], v[222:225], v[4:7]
	v_mfma_f32_16x16x32_bf16 v[8:11], v[180:183], v[226:229], v[8:11]
	v_mfma_f32_16x16x32_bf16 v[148:151], v[180:183], v[180:183], v[148:151]
	v_mfma_f32_16x16x32_bf16 v[12:15], v[180:183], v[230:233], v[12:15]
	v_mfma_f32_16x16x32_bf16 v[16:19], v[180:183], v[234:237], v[16:19]
	v_mfma_f32_16x16x32_bf16 v[20:23], v[180:183], v[238:241], v[20:23]
	v_mfma_f32_16x16x32_bf16 v[24:27], v[180:183], v[242:245], v[24:27]
	v_mfma_f32_16x16x32_bf16 v[28:31], v[180:183], v[246:249], v[28:31]
	ds_read_b128 v[180:183], v194 offset:40960
	v_mfma_f32_16x16x32_bf16 v[32:35], v[200:203], v[204:207], v[32:35]
	ds_read_b128 v[204:207], v195 offset:36864
	v_mfma_f32_16x16x32_bf16 v[36:39], v[200:203], v[222:225], v[36:39]
	ds_read_b128 v[222:225], v195 offset:38912
	v_mfma_f32_16x16x32_bf16 v[40:43], v[200:203], v[226:229], v[40:43]
	v_mfma_f32_16x16x32_bf16 v[152:155], v[200:203], v[200:203], v[152:155]
	ds_read_b128 v[226:229], v195 offset:40960
	v_mfma_f32_16x16x32_bf16 v[44:47], v[200:203], v[230:233], v[44:47]
	ds_read_b128 v[230:233], v195 offset:43008
	v_mfma_f32_16x16x32_bf16 v[48:51], v[200:203], v[234:237], v[48:51]
	ds_read_b128 v[234:237], v195 offset:45056
	v_mfma_f32_16x16x32_bf16 v[52:55], v[200:203], v[238:241], v[52:55]
	ds_read_b128 v[238:241], v195 offset:47104
	v_mfma_f32_16x16x32_bf16 v[56:59], v[200:203], v[242:245], v[56:59]
	ds_read_b128 v[242:245], v195 offset:49152
	v_mfma_f32_16x16x32_bf16 v[60:63], v[200:203], v[246:249], v[60:63]
	ds_read_b128 v[246:249], v195 offset:51200
	ds_read_b128 v[200:203], v194 offset:43008
	s_waitcnt lgkmcnt(8)
	v_mfma_f32_16x16x32_bf16 v[64:67], v[160:163], v[204:207], v[64:67]
	s_waitcnt lgkmcnt(7)
	v_mfma_f32_16x16x32_bf16 v[68:71], v[160:163], v[222:225], v[68:71]
	s_waitcnt lgkmcnt(6)
	v_mfma_f32_16x16x32_bf16 v[72:75], v[160:163], v[226:229], v[72:75]
	s_waitcnt lgkmcnt(5)
	v_mfma_f32_16x16x32_bf16 v[76:79], v[160:163], v[230:233], v[76:79]
	s_waitcnt lgkmcnt(4)
	v_mfma_f32_16x16x32_bf16 v[80:83], v[160:163], v[234:237], v[80:83]
	s_waitcnt lgkmcnt(3)
	v_mfma_f32_16x16x32_bf16 v[84:87], v[160:163], v[238:241], v[84:87]
	s_waitcnt lgkmcnt(2)
	v_mfma_f32_16x16x32_bf16 v[88:91], v[160:163], v[242:245], v[88:91]
	s_waitcnt lgkmcnt(1)
	v_mfma_f32_16x16x32_bf16 v[92:95], v[160:163], v[246:249], v[92:95]
	ds_read_b128 v[160:163], v215 offset:36864
	v_mfma_f32_16x16x32_bf16 v[96:99], v[176:179], v[204:207], v[96:99]
	v_mfma_f32_16x16x32_bf16 v[100:103], v[176:179], v[222:225], v[100:103]
	v_mfma_f32_16x16x32_bf16 v[104:107], v[176:179], v[226:229], v[104:107]
	v_mfma_f32_16x16x32_bf16 v[108:111], v[176:179], v[230:233], v[108:111]
	v_mfma_f32_16x16x32_bf16 v[112:115], v[176:179], v[234:237], v[112:115]
	v_mfma_f32_16x16x32_bf16 v[116:119], v[176:179], v[238:241], v[116:119]
	v_mfma_f32_16x16x32_bf16 v[120:123], v[176:179], v[242:245], v[120:123]
	v_mfma_f32_16x16x32_bf16 v[124:127], v[176:179], v[246:249], v[124:127]
	ds_read_b128 v[176:179], v215 offset:38912
	v_mfma_f32_16x16x32_bf16 v[0:3], v[180:183], v[204:207], v[0:3]
	v_mfma_f32_16x16x32_bf16 v[4:7], v[180:183], v[222:225], v[4:7]
	v_mfma_f32_16x16x32_bf16 v[8:11], v[180:183], v[226:229], v[8:11]
	v_mfma_f32_16x16x32_bf16 v[12:15], v[180:183], v[230:233], v[12:15]
	v_mfma_f32_16x16x32_bf16 v[16:19], v[180:183], v[234:237], v[16:19]
	v_mfma_f32_16x16x32_bf16 v[20:23], v[180:183], v[238:241], v[20:23]
	v_mfma_f32_16x16x32_bf16 v[24:27], v[180:183], v[242:245], v[24:27]
	v_mfma_f32_16x16x32_bf16 v[28:31], v[180:183], v[246:249], v[28:31]
	ds_read_b128 v[180:183], v215 offset:40960
	s_waitcnt lgkmcnt(3)
; DI void lds_barrier() { asm volatile("s_waitcnt lgkmcnt(0)\n\ts_barrier" ::: "memory"); }
; DI void gemm_run(const GemmCfg c, char* smem, float* const g_h, u16* const g_hb, float* const g_out, const int final_out) {
;     ...
;     K_STEP(0, 1, 0, true, false);
;     lds_barrier();
;     K_STEP(1, 0, 0, false, false);
;     lds_barrier();
	v_mfma_f32_16x16x32_bf16 v[32:35], v[200:203], v[204:207], v[32:35]
	ds_read_b128 v[204:207], v197 offset:36864
	v_mfma_f32_16x16x32_bf16 v[36:39], v[200:203], v[222:225], v[36:39]
	ds_read_b128 v[222:225], v197 offset:38912
	v_mfma_f32_16x16x32_bf16 v[40:43], v[200:203], v[226:229], v[40:43]
	ds_read_b128 v[226:229], v197 offset:40960
	v_mfma_f32_16x16x32_bf16 v[44:47], v[200:203], v[230:233], v[44:47]
	ds_read_b128 v[230:233], v197 offset:43008
	v_mfma_f32_16x16x32_bf16 v[48:51], v[200:203], v[234:237], v[48:51]
	ds_read_b128 v[234:237], v197 offset:45056
	v_mfma_f32_16x16x32_bf16 v[52:55], v[200:203], v[238:241], v[52:55]
	ds_read_b128 v[238:241], v197 offset:47104
	v_mfma_f32_16x16x32_bf16 v[56:59], v[200:203], v[242:245], v[56:59]
	ds_read_b128 v[242:245], v197 offset:49152
	v_mfma_f32_16x16x32_bf16 v[60:63], v[200:203], v[246:249], v[60:63]
	ds_read_b128 v[246:249], v197 offset:51200
	ds_read_b128 v[200:203], v215 offset:43008
	s_waitcnt lgkmcnt(8)
	v_mfma_f32_16x16x32_bf16 v[64:67], v[160:163], v[204:207], v[64:67]
	s_waitcnt lgkmcnt(7)
	v_mfma_f32_16x16x32_bf16 v[68:71], v[160:163], v[222:225], v[68:71]
	s_waitcnt lgkmcnt(6)
	v_mfma_f32_16x16x32_bf16 v[72:75], v[160:163], v[226:229], v[72:75]
	v_mfma_f32_16x16x32_bf16 v[140:143], v[160:163], v[160:163], v[140:143]
	s_waitcnt lgkmcnt(5)
	v_mfma_f32_16x16x32_bf16 v[76:79], v[160:163], v[230:233], v[76:79]
	s_waitcnt lgkmcnt(4)
	v_mfma_f32_16x16x32_bf16 v[80:83], v[160:163], v[234:237], v[80:83]
	s_waitcnt lgkmcnt(3)
	v_mfma_f32_16x16x32_bf16 v[84:87], v[160:163], v[238:241], v[84:87]
	s_waitcnt lgkmcnt(2)
	v_mfma_f32_16x16x32_bf16 v[88:91], v[160:163], v[242:245], v[88:91]
	s_waitcnt lgkmcnt(1)
	v_mfma_f32_16x16x32_bf16 v[92:95], v[160:163], v[246:249], v[92:95]
	v_mfma_f32_16x16x32_bf16 v[96:99], v[176:179], v[204:207], v[96:99]
	v_mfma_f32_16x16x32_bf16 v[100:103], v[176:179], v[222:225], v[100:103]
	v_mfma_f32_16x16x32_bf16 v[104:107], v[176:179], v[226:229], v[104:107]
	v_mfma_f32_16x16x32_bf16 v[144:147], v[176:179], v[176:179], v[144:147]
	v_mfma_f32_16x16x32_bf16 v[108:111], v[176:179], v[230:233], v[108:111]
	v_mfma_f32_16x16x32_bf16 v[112:115], v[176:179], v[234:237], v[112:115]
	v_mfma_f32_16x16x32_bf16 v[116:119], v[176:179], v[238:241], v[116:119]
	v_mfma_f32_16x16x32_bf16 v[120:123], v[176:179], v[242:245], v[120:123]
	v_mfma_f32_16x16x32_bf16 v[124:127], v[176:179], v[246:249], v[124:127]
	v_mfma_f32_16x16x32_bf16 v[0:3], v[180:183], v[204:207], v[0:3]
	v_mfma_f32_16x16x32_bf16 v[4:7], v[180:183], v[222:225], v[4:7]
	v_mfma_f32_16x16x32_bf16 v[8:11], v[180:183], v[226:229], v[8:11]
	v_mfma_f32_16x16x32_bf16 v[148:151], v[180:183], v[180:183], v[148:151]
	v_mfma_f32_16x16x32_bf16 v[12:15], v[180:183], v[230:233], v[12:15]
	v_mfma_f32_16x16x32_bf16 v[16:19], v[180:183], v[234:237], v[16:19]
	v_mfma_f32_16x16x32_bf16 v[20:23], v[180:183], v[238:241], v[20:23]
	v_mfma_f32_16x16x32_bf16 v[24:27], v[180:183], v[242:245], v[24:27]
	v_mfma_f32_16x16x32_bf16 v[28:31], v[180:183], v[246:249], v[28:31]
	s_waitcnt lgkmcnt(0)
	v_mfma_f32_16x16x32_bf16 v[32:35], v[200:203], v[204:207], v[32:35]
	v_mfma_f32_16x16x32_bf16 v[36:39], v[200:203], v[222:225], v[36:39]
	v_mfma_f32_16x16x32_bf16 v[40:43], v[200:203], v[226:229], v[40:43]
	v_mfma_f32_16x16x32_bf16 v[152:155], v[200:203], v[200:203], v[152:155]
	v_mfma_f32_16x16x32_bf16 v[44:47], v[200:203], v[230:233], v[44:47]
	v_mfma_f32_16x16x32_bf16 v[48:51], v[200:203], v[234:237], v[48:51]
	v_mfma_f32_16x16x32_bf16 v[52:55], v[200:203], v[238:241], v[52:55]
	v_mfma_f32_16x16x32_bf16 v[56:59], v[200:203], v[242:245], v[56:59]
	v_mfma_f32_16x16x32_bf16 v[60:63], v[200:203], v[246:249], v[60:63]
	s_branch .Lgemm_kdone

; DI float shx(float v, int mask, int lane) { return __int_as_float(__builtin_amdgcn_ds_bpermute((lane ^ mask) << 2, __float_as_int(v))); }
; DI void gemm_run(const GemmCfg c, char* smem, float* const g_h, u16* const g_hb, float* const g_out, const int final_out) {
;     ...
;     if (c.use_rs) {
; #pragma unroll
;       for (int i = 0; i < 4; ++i) {
;         float s_ = ss[i];
;         s_ += shx(s_, 1, lane); s_ += shx(s_, 2, lane); s_ += shx(s_, 4, lane);
;         if (lch == 0) s_rowss[lrow + 64 * i] = s_;
;       }
;     }
;     __syncthreads();
.Lgemm_kdone:
	s_waitcnt lgkmcnt(0)
	s_barrier
	s_lshl_b32 s0, s49, 8
	v_cndmask_b32_e64 v136, 0, 1, s[88:89]
	v_cmp_ne_u32_e64 s[42:43], 1, v136
	s_cmp_lg_u32 s9, 0
	s_cbranch_scc0 .LBB0_124
	v_and_b32_e32 v128, 15, v185
	v_lshrrev_b32_e32 v129, 4, v185
	v_lshrrev_b32_e32 v130, 2, v128
	v_and_b32_e32 v131, 3, v128
	v_cmp_eq_u32_e64 s[4:5], 1, v131
	v_cmp_eq_u32_e64 s[6:7], 2, v131
	v_cmp_eq_u32_e64 s[8:9], 3, v131
	v_cmp_eq_u32_e32 vcc, v129, v130
	s_nop 1
	v_cndmask_b32_e64 v132, v140, v141, s[4:5]
	v_cndmask_b32_e64 v132, v132, v142, s[6:7]
	v_cndmask_b32_e64 v132, v132, v143, s[8:9]
	v_cndmask_b32_e64 v133, v144, v145, s[4:5]
	v_cndmask_b32_e64 v133, v133, v146, s[6:7]
	v_cndmask_b32_e64 v133, v133, v147, s[8:9]
	v_cndmask_b32_e64 v134, v148, v149, s[4:5]
	v_cndmask_b32_e64 v134, v134, v150, s[6:7]
	v_cndmask_b32_e64 v134, v134, v151, s[8:9]
	v_cndmask_b32_e64 v135, v152, v153, s[4:5]
	v_cndmask_b32_e64 v135, v135, v154, s[6:7]
	v_cndmask_b32_e64 v135, v135, v155, s[8:9]
	s_lshl_b32 s1, s86, 2
	s_add_i32 s1, s1, 0x24000
	v_lshl_add_u32 v128, v128, 2, s1
	s_and_saveexec_b64 s[4:5], vcc
	ds_add_f32 v128, v132
	ds_add_f32 v128, v133 offset:64
	ds_add_f32 v128, v134 offset:128
	ds_add_f32 v128, v135 offset:192
	s_or_b64 exec, exec, s[4:5]

; DI void xcd_barrier(const XcdBarrier& b) {
;   asm volatile("s_waitcnt vmcnt(0)" ::: "memory");
;   __syncthreads();
;   if (threadIdx.x == 0) {
;     unsigned* bar = b.bar;
;     __builtin_amdgcn_s_waitcnt(0);
;     unsigned nloc = b.st[0], nx = b.st[1];
;     if (nloc == 0u) { xcd_barrier_complete(bar, b.x, nloc, nx); b.st[0] = nloc; b.st[1] = nx; }
; __global__ void __launch_bounds__(NT, 2) mega(Params p) {
;     ...
;       if (layer == 0 && st == 0) grid.sync();
;       else xcd_barrier(xb);
.LBB0_921:
	v_readlane_b32 s0, v254, 38
	v_readlane_b32 s1, v254, 34
	v_readlane_b32 s24, v254, 24
	s_or_b32 s0, s1, s0
	v_readlane_b32 s25, v254, 25
	s_cmp_lg_u32 s0, 0
	v_readlane_b32 s26, v254, 26
	v_readlane_b32 s27, v254, 27
	s_nop 0
	s_waitcnt vmcnt(0)
	s_waitcnt lgkmcnt(0)
	s_barrier
	s_mov_b64 s[0:1], exec
	v_readlane_b32 s4, v252, 4
	v_readlane_b32 s5, v252, 5
	s_and_b64 s[4:5], s[0:1], s[4:5]
	s_mov_b64 exec, s[4:5]
	s_cbranch_execz .LBB0_975
	s_waitcnt vmcnt(0) expcnt(0) lgkmcnt(0)
	ds_read_b32 v2, v212
	ds_read_b32 v0, v213
	s_waitcnt lgkmcnt(1)
	v_cmp_ne_u32_e32 vcc, 0, v2
	s_cbranch_vccnz .LBB0_939
	s_mov_b32 s2, 1
	s_branch .LBB0_926
